# EpiLru counted first wait; pass1 unit prologue dt loads issued together; ml_conv history-row loads merged under one wait
# baseline (speedup 1.0000x reference)
.LBB0_589:
	s_or_b64 exec, exec, s[4:5]
	s_mov_b64 s[4:5], -1
	s_and_b64 vcc, exec, s[2:3]
	s_waitcnt lgkmcnt(0)
	s_barrier
	s_cbranch_vccz .LBB0_925
	s_mov_b64 s[8:9], s[66:67]
	s_load_dwordx2 s[2:3], s[8:9], 0x120
	s_load_dwordx4 s[4:7], s[8:9], 0xc0
	v_mov_b32_e32 v172, v178
	v_mov_b32_e32 v15, v0
	v_lshlrev_b32_e32 v1, 3, v172
	v_and_b32_e32 v170, 0x7f8, v1
	v_lshlrev_b32_e32 v14, 2, v170
	s_waitcnt lgkmcnt(0)
	v_lshl_add_u64 v[34:35], s[4:5], 0, v[14:15]
	global_load_dwordx4 v[2:5], v14, s[6:7] offset:16
	global_load_dwordx4 v[6:9], v14, s[4:5] offset:16
	global_load_dwordx4 v[10:13], v14, s[6:7]
	s_nop 0
	global_load_dwordx4 v[14:17], v14, s[4:5]
	s_mov_b64 s[4:5], 0x2000
	v_lshl_add_u64 v[22:23], v[34:35], 0, s[4:5]
	s_movk_i32 s4, 0x2000
	v_add_co_u32_e32 v18, vcc, s4, v34
	s_mov_b64 s[4:5], 0x4000
	s_nop 0
	v_addc_co_u32_e32 v19, vcc, 0, v35, vcc
	v_add_co_u32_e32 v26, vcc, s34, v34
	s_add_u32 s8, s2, 0x3080000
	v_lshl_add_u64 v[30:31], v[34:35], 0, s[4:5]
	v_addc_co_u32_e32 v27, vcc, 0, v35, vcc
	s_mov_b64 s[4:5], 0x6000
	s_addc_u32 s9, s3, 0
	v_lshl_add_u64 v[38:39], v[34:35], 0, s[4:5]
	v_add_co_u32_e32 v34, vcc, s31, v34
	v_lshlrev_b32_e32 v138, 5, v170
	v_mov_b32_e32 v139, v0
	v_addc_co_u32_e32 v35, vcc, 0, v35, vcc
	v_lshl_add_u64 v[58:59], s[8:9], 0, v[138:139]
	s_mov_b64 s[4:5], 0x10000
	v_lshl_add_u64 v[70:71], v[58:59], 0, s[4:5]
	v_add_co_u32_e32 v58, vcc, s35, v58
	v_or_b32_e32 v86, 64, v138
	v_mov_b32_e32 v87, v0
	v_addc_co_u32_e32 v59, vcc, 0, v59, vcc
	v_lshl_add_u64 v[90:91], s[8:9], 0, v[86:87]
	v_lshl_add_u64 v[102:103], v[90:91], 0, s[4:5]
	v_add_co_u32_e32 v90, vcc, s35, v90
	v_or_b32_e32 v118, 0x80, v138
	v_mov_b32_e32 v119, v0
	v_addc_co_u32_e32 v91, vcc, 0, v91, vcc
	v_lshl_add_u64 v[122:123], s[8:9], 0, v[118:119]
	v_lshl_add_u64 v[134:135], v[122:123], 0, s[4:5]
	v_add_co_u32_e32 v122, vcc, s35, v122
	v_or_b32_e32 v150, 0xc0, v138
	v_mov_b32_e32 v151, v0
	v_addc_co_u32_e32 v123, vcc, 0, v123, vcc
	v_lshl_add_u64 v[154:155], s[8:9], 0, v[150:151]
	v_lshl_add_u64 v[166:167], v[154:155], 0, s[4:5]
	v_add_co_u32_e32 v154, vcc, s35, v154
	global_load_dwordx4 v[18:21], v[18:19], off
	s_nop 0
	global_load_dwordx4 v[22:25], v[22:23], off offset:16
	v_addc_co_u32_e32 v155, vcc, 0, v155, vcc
	global_load_dwordx4 v[26:29], v[26:27], off
	s_nop 0
	global_load_dwordx4 v[30:33], v[30:31], off offset:16
	s_nop 0
	global_load_dwordx4 v[34:37], v[34:35], off
	s_nop 0
	global_load_dwordx4 v[38:41], v[38:39], off offset:16
	s_nop 0
	global_load_dwordx4 v[42:45], v138, s[8:9] offset:48
	global_load_dwordx4 v[46:49], v138, s[8:9] offset:32
	global_load_dwordx4 v[50:53], v138, s[8:9] offset:16
	global_load_dwordx4 v[54:57], v138, s[8:9]
	s_nop 0
	global_load_dwordx4 v[58:61], v[58:59], off
	s_nop 0
	global_load_dwordx4 v[62:65], v[70:71], off offset:48
	global_load_dwordx4 v[66:69], v[70:71], off offset:32
	s_nop 0
	global_load_dwordx4 v[70:73], v[70:71], off offset:16
	s_nop 0
	global_load_dwordx4 v[74:77], v86, s[8:9] offset:48
	global_load_dwordx4 v[78:81], v86, s[8:9] offset:32
	global_load_dwordx4 v[82:85], v86, s[8:9] offset:16
	s_nop 0
	global_load_dwordx4 v[86:89], v86, s[8:9]
	s_nop 0
	global_load_dwordx4 v[90:93], v[90:91], off
	s_nop 0
	global_load_dwordx4 v[94:97], v[102:103], off offset:48
	global_load_dwordx4 v[98:101], v[102:103], off offset:32
	s_nop 0
	global_load_dwordx4 v[102:105], v[102:103], off offset:16
	s_nop 0
	global_load_dwordx4 v[106:109], v118, s[8:9] offset:48
	global_load_dwordx4 v[110:113], v118, s[8:9] offset:32
	global_load_dwordx4 v[114:117], v118, s[8:9] offset:16
	s_nop 0
	global_load_dwordx4 v[118:121], v118, s[8:9]
	s_nop 0
	global_load_dwordx4 v[122:125], v[122:123], off
	s_nop 0
	global_load_dwordx4 v[126:129], v[134:135], off offset:48
	global_load_dwordx4 v[130:133], v[134:135], off offset:32
	s_nop 0
	global_load_dwordx4 v[134:137], v[134:135], off offset:16
	s_nop 0
	global_load_dwordx4 v[138:141], v150, s[8:9] offset:48
	global_load_dwordx4 v[142:145], v150, s[8:9] offset:32
	global_load_dwordx4 v[146:149], v150, s[8:9] offset:16
	s_nop 0
	global_load_dwordx4 v[150:153], v150, s[8:9]
	s_nop 0
	global_load_dwordx4 v[154:157], v[154:155], off
	s_nop 0
	global_load_dwordx4 v[158:161], v[166:167], off offset:48
	global_load_dwordx4 v[162:165], v[166:167], off offset:32
	s_nop 0
	global_load_dwordx4 v[166:169], v[166:167], off offset:16
	s_mov_b32 s4, s70
	s_add_u32 s8, s2, 0x3200000
	s_addc_u32 s9, s3, 0
	s_lshl_b32 s4, s4, 1
	s_abs_i32 s5, s4
	v_cvt_f32_u32_e32 v1, s5
	s_sub_i32 s6, 0, s5
	s_ashr_i32 s4, s4, 31
	v_ashrrev_i32_e32 v171, 8, v172
	v_rcp_iflag_f32_e32 v1, v1
	v_mov_b32_e32 v193, 0
	v_lshlrev_b32_e32 v170, 1, v170
	v_mov_b32_e32 v192, 0
	v_mul_f32_e32 v1, 0x4f7ffffe, v1
	v_cvt_u32_f32_e32 v1, v1
	v_mov_b32_e32 v194, 0
	v_mov_b32_e32 v196, 0
	v_mov_b32_e32 v198, 0
	v_readfirstlane_b32 s7, v1
	s_mul_i32 s6, s6, s7
	s_mul_hi_u32 s6, s7, s6
	s_add_i32 s7, s7, s6
	s_lshr_b32 s6, s7, 17
	s_mul_i32 s7, s6, s5
	s_sub_i32 s7, 0x8000, s7
	s_add_i32 s10, s6, 1
	s_sub_i32 s11, s7, s5
	s_cmp_ge_u32 s7, s5
	s_cselect_b32 s6, s10, s6
	s_cselect_b32 s7, s11, s7
	s_add_i32 s10, s6, 1
	s_cmp_ge_u32 s7, s5
	s_cselect_b32 s5, s10, s6
	s_xor_b32 s5, s5, s4
	s_sub_i32 s12, s5, s4
	s_mov_b32 s4, s68
	v_mov_b32_e32 v200, 0
	v_lshl_add_u32 v1, s4, 1, v171
	v_mul_lo_u32 v190, v1, s12
	v_and_b32_e32 v1, 0x1fff, v190
	v_cmp_lt_u32_e32 vcc, 2, v1
	v_ashrrev_i32_e32 v191, 31, v190
	v_mov_b32_e32 v202, 0
	v_mov_b32_e32 v204, 0
	v_mov_b32_e32 v206, 0
	v_mov_b32_e32 v174, 0
	v_mov_b32_e32 v175, 0
	v_mov_b32_e32 v176, 0
	v_mov_b32_e32 v177, 0
	v_mov_b32_e32 v236, 0
	v_mov_b32_e32 v237, 0
	v_mov_b32_e32 v238, 0
	v_mov_b32_e32 v239, 0
	v_mov_b32_e32 v246, 0
	v_mov_b32_e32 v247, 0
	v_mov_b32_e32 v248, 0
	v_mov_b32_e32 v249, 0
	s_and_saveexec_b64 s[4:5], vcc
	s_cbranch_execz .LBB0_592
	v_lshlrev_b64 v[174:175], 13, v[190:191]
	v_lshl_add_u64 v[174:175], s[8:9], 0, v[174:175]
	v_mov_b32_e32 v171, v0
	v_lshl_add_u64 v[174:175], v[174:175], 0, v[170:171]
	v_add_co_u32_e32 v174, vcc, 0xffffa000, v174
	s_nop 1
	v_addc_co_u32_e32 v175, vcc, -1, v175, vcc
	global_load_dwordx4 v[174:177], v[174:175], off
.LBB0_592:
	s_or_b64 exec, exec, s[4:5]
	v_cmp_lt_u32_e32 vcc, 1, v1
	v_mov_b32_e32 v195, 0
	v_mov_b32_e32 v197, 0
	v_mov_b32_e32 v199, 0
	v_mov_b32_e32 v201, 0
	v_mov_b32_e32 v203, 0
	v_mov_b32_e32 v205, 0
	v_mov_b32_e32 v207, 0
	s_and_saveexec_b64 s[4:5], vcc
	s_cbranch_execz .LBB0_594
	v_lshlrev_b64 v[250:251], 13, v[190:191]
	v_lshl_add_u64 v[250:251], s[8:9], 0, v[250:251]
	v_mov_b32_e32 v171, v0
	v_lshl_add_u64 v[250:251], v[250:251], 0, v[170:171]
	v_add_co_u32_e32 v250, vcc, 0xffffc000, v250
	s_nop 1
	v_addc_co_u32_e32 v251, vcc, -1, v251, vcc
	global_load_dwordx4 v[236:239], v[250:251], off
.LBB0_594:
	s_or_b64 exec, exec, s[4:5]
	v_cmp_ne_u32_e32 vcc, 0, v1
	v_mov_b32_e32 v208, 0
	v_mov_b32_e32 v210, 0
	v_mov_b32_e32 v212, 0
	v_mov_b32_e32 v214, 0
	v_mov_b32_e32 v216, 0
	v_mov_b32_e32 v218, 0
	v_mov_b32_e32 v220, 0
	v_mov_b32_e32 v222, 0
	s_and_saveexec_b64 s[4:5], vcc
	s_cbranch_execz .LBB0_596
	v_lshlrev_b64 v[252:253], 13, v[190:191]
	v_lshl_add_u64 v[252:253], s[8:9], 0, v[252:253]
	v_mov_b32_e32 v171, v0
	v_lshl_add_u64 v[252:253], v[252:253], 0, v[170:171]
	v_add_co_u32_e32 v252, vcc, 0xffffe000, v252
	s_nop 1
	v_addc_co_u32_e32 v253, vcc, -1, v253, vcc
	global_load_dwordx4 v[246:249], v[252:253], off
.LBB0_596:
	s_or_b64 exec, exec, s[4:5]
	s_waitcnt vmcnt(0)
	v_lshlrev_b32_e32 v192, 16, v174
	v_and_b32_e32 v194, 0xffff0000, v174
	v_lshlrev_b32_e32 v196, 16, v175
	v_and_b32_e32 v198, 0xffff0000, v175
	v_lshlrev_b32_e32 v200, 16, v176
	v_and_b32_e32 v202, 0xffff0000, v176
	v_lshlrev_b32_e32 v204, 16, v177
	v_and_b32_e32 v206, 0xffff0000, v177
	v_lshlrev_b32_e32 v193, 16, v236
	v_and_b32_e32 v195, 0xffff0000, v236
	v_lshlrev_b32_e32 v197, 16, v237
	v_and_b32_e32 v199, 0xffff0000, v237
	v_lshlrev_b32_e32 v201, 16, v238
	v_and_b32_e32 v203, 0xffff0000, v238
	v_lshlrev_b32_e32 v205, 16, v239
	v_and_b32_e32 v207, 0xffff0000, v239
	v_lshlrev_b32_e32 v208, 16, v246
	v_and_b32_e32 v210, 0xffff0000, v246
	v_lshlrev_b32_e32 v212, 16, v247
	v_and_b32_e32 v214, 0xffff0000, v247
	v_lshlrev_b32_e32 v216, 16, v248
	v_and_b32_e32 v218, 0xffff0000, v248
	v_lshlrev_b32_e32 v220, 16, v249
	v_and_b32_e32 v222, 0xffff0000, v249
	s_cmp_lt_i32 s12, 1
	s_cbranch_scc1 .LBB0_605
	v_lshlrev_b64 v[174:175], 13, v[190:191]
	v_mov_b32_e32 v171, v0
	v_lshl_add_u64 v[174:175], s[8:9], 0, v[174:175]
	v_lshl_add_u64 v[174:175], v[174:175], 0, v[170:171]
	global_load_dwordx4 v[174:177], v[174:175], off
	v_and_b32_e32 v1, 32, v172
	v_cmp_eq_u32_e32 vcc, 0, v1
	v_and_b32_e32 v1, 16, v172
	v_cmp_eq_u32_e64 s[4:5], 0, v1
	v_and_b32_e32 v1, 8, v172
	v_lshl_add_u64 v[224:225], s[8:9], 0, v[170:171]
	v_cmp_lt_i32_e64 s[8:9], v241, v235
	v_cmp_eq_u32_e64 s[6:7], 0, v1
	s_waitcnt vmcnt(39)
	v_mov_b32_e32 v170, v15
	v_cndmask_b32_e64 v1, v234, v241, s[8:9]
	v_cmp_lt_i32_e64 s[8:9], v240, v235
	v_mov_b32_e32 v173, v7
	s_waitcnt vmcnt(34)
	v_mov_b32_e32 v7, v35
	v_cndmask_b32_e64 v15, v234, v240, s[8:9]
	v_lshlrev_b32_e32 v247, 2, v15
	v_xor_b32_e32 v15, 8, v234
	v_cmp_lt_i32_e64 s[8:9], v15, v235
	v_mov_b32_e32 v171, v17
	v_mov_b32_e32 v186, v9
	v_cndmask_b32_e64 v15, v234, v15, s[8:9]
	v_lshlrev_b32_e32 v248, 2, v15
	v_xor_b32_e32 v15, 4, v234
	v_cmp_lt_i32_e64 s[8:9], v15, v235
	v_mov_b32_e32 v9, v37
	v_mov_b32_e32 v35, v26
	v_cndmask_b32_e64 v15, v234, v15, s[8:9]
	v_lshlrev_b32_e32 v249, 2, v15
	v_xor_b32_e32 v15, 2, v234
	v_cmp_lt_i32_e64 s[8:9], v15, v235
	v_mov_b32_e32 v26, v7
	v_mov_b32_e32 v7, v22
	v_cndmask_b32_e64 v15, v234, v15, s[8:9]
	v_lshlrev_b32_e32 v250, 2, v15
	v_xor_b32_e32 v15, 1, v234
	v_cmp_lt_i32_e64 s[8:9], v15, v235
	v_mov_b32_e32 v22, v173
	v_lshrrev_b32_e32 v173, 1, v172
	v_cndmask_b32_e64 v15, v234, v15, s[8:9]
	v_lshlrev_b32_e32 v251, 2, v15
	v_and_b32_e32 v15, 7, v172
	v_cmp_eq_u32_e64 s[8:9], 0, v15
	v_mov_b32_e32 v15, v18
	v_mov_b32_e32 v18, v170
	v_mov_b32_e32 v17, v20
	v_mov_b32_e32 v37, v28
	v_mov_b32_e32 v20, v171
	v_mov_b32_e32 v28, v9
	v_mov_b32_e32 v9, v24
	v_mov_b32_e32 v24, v186
	v_lshlrev_b64 v[170:171], 7, v[190:191]
	v_and_b32_e32 v186, 0x60, v173
	v_and_b32_e32 v173, 28, v173
	v_or3_b32 v170, v170, v186, v173
	v_lshl_add_u64 v[170:171], s[2:3], 0, v[170:171]
	s_mov_b64 s[10:11], 0x1c200000
	v_lshl_add_u64 v[226:227], v[170:171], 0, s[10:11]
	v_lshlrev_b64 v[170:171], 12, v[190:191]
	v_and_b32_e32 v172, 0xff, v172
	v_lshl_or_b32 v170, v172, 4, v170
	s_waitcnt vmcnt(33)
	v_mov_b32_e32 v187, v39
	v_mov_b32_e32 v188, v41
	v_lshl_add_u64 v[170:171], s[2:3], 0, v[170:171]
	s_mov_b64 s[2:3], 0x13200000
	s_mov_b32 s13, 0
	v_lshlrev_b32_e32 v1, 2, v1
	v_mov_b32_e32 v39, v30
	v_mov_b32_e32 v30, v187
	v_mov_b32_e32 v41, v32
	v_mov_b32_e32 v32, v188
	v_lshl_add_u64 v[228:229], v[170:171], 0, s[2:3]
	s_waitcnt vmcnt(0)
	s_branch .LBB0_599

.LBB0_929:
	s_and_b32 s14, s46, 1
	s_waitcnt vmcnt(0)
	v_mov_b32_e32 v40, v178
	v_mov_b32_e32 v1, v178
	s_lshl_b32 s33, s14, 3
	v_ashrrev_i32_e32 v4, 6, v1
	v_add_u32_e32 v2, s33, v4
	v_ashrrev_i32_e32 v3, 31, v2
	v_lshlrev_b64 v[6:7], 2, v[2:3]
	v_mov_b32_e32 v1, v178
	v_lshl_add_u64 v[8:9], s[26:27], 0, v[6:7]
	global_load_dword v3, v[8:9], off
	s_ashr_i32 s38, s46, 7
	s_bfe_u32 s47, s46, 0x60001
	s_ashr_i32 s39, s38, 31
	s_lshl_b64 s[8:9], s[38:39], 13
	s_lshl_b32 s10, s47, 7
	s_or_b32 s6, s8, s10
	v_and_b32_e32 v1, 63, v1
	v_lshl_add_u64 v[8:9], s[24:25], 0, v[6:7]
	global_load_dword v5, v[8:9], off
	v_or_b32_e32 v8, s6, v1
	v_mov_b32_e32 v9, s9
	v_lshlrev_b64 v[8:9], 6, v[8:9]
	v_lshl_add_u64 v[8:9], s[30:31], 0, v[8:9]
	v_lshl_add_u64 v[6:7], v[8:9], 0, v[6:7]
	global_load_dword v107, v[6:7], off
	v_mov_b32_e32 v112, s69
	v_mov_b32_e32 v113, 0
	v_lshl_add_u64 v[110:111], v[6:7], 0, v[112:113]
	global_load_dword v108, v[110:111], off
	s_waitcnt vmcnt(3)
	v_mul_f32_e32 v3, 0x3fb8aa3b, v3
	v_exp_f32_e32 v10, v3
	s_waitcnt vmcnt(1)
	v_mov_b32_e32 v3, v107
	v_add_f32_e32 v3, v5, v3
	v_max_f32_e32 v8, 0, v3
	v_mul_f32_e64 v3, |v3|, s72
	v_exp_f32_e32 v3, v3
	s_nop 0
	v_add_f32_e32 v3, 1.0, v3
	v_cmp_gt_f32_e32 vcc, s71, v3
	s_nop 1
	v_cndmask_b32_e64 v9, 0, 32, vcc
	v_ldexp_f32 v3, v3, v9
	v_log_f32_e32 v3, v3
	s_nop 0
	v_mul_f32_e32 v9, 0x3f317217, v3
	v_fma_f32 v9, v3, s73, -v9
	v_fmac_f32_e32 v9, 0x3377d1cf, v3
	v_fmac_f32_e32 v9, 0x3f317217, v3
	v_cmp_lt_f32_e64 s[4:5], |v3|, s74
	s_nop 1
	v_cndmask_b32_e64 v3, v3, v9, s[4:5]
	v_cndmask_b32_e32 v9, 0, v243, vcc
	v_add_co_u32_e32 v6, vcc, s69, v6
	v_sub_f32_e32 v3, v3, v9
	s_nop 0
	v_addc_co_u32_e32 v7, vcc, 0, v7, vcc
	v_add_f32_e32 v3, v8, v3
	v_add_u32_e32 v8, -1, v234
	s_waitcnt vmcnt(0)
	v_mov_b32_e32 v6, v108
	v_add_f32_e32 v5, v5, v6
	v_max_f32_e32 v6, 0, v5
	v_mul_f32_e64 v5, |v5|, s72
	v_exp_f32_e32 v5, v5
	s_nop 0
	v_add_f32_e32 v5, 1.0, v5
	v_cmp_gt_f32_e32 vcc, s71, v5
	s_nop 1
	v_cndmask_b32_e64 v7, 0, 32, vcc
	v_ldexp_f32 v5, v5, v7
	v_log_f32_e32 v5, v5
	s_nop 0
	v_mul_f32_e32 v7, 0x3f317217, v5
	v_fma_f32 v7, v5, s73, -v7
	v_fmac_f32_e32 v7, 0x3377d1cf, v5
	v_fmac_f32_e32 v7, 0x3f317217, v5
	v_cmp_lt_f32_e64 s[4:5], |v5|, s74
	s_nop 1
	v_cndmask_b32_e64 v5, v5, v7, s[4:5]
	v_cndmask_b32_e32 v7, 0, v243, vcc
	v_sub_f32_e32 v5, v5, v7
	v_cmp_lt_i32_e32 vcc, v8, v242
	v_add_f32_e32 v5, v6, v5
	v_mul_f32_e64 v6, v3, -v10
	v_cndmask_b32_e32 v8, v8, v234, vcc
	v_mul_f32_e64 v7, v5, -v10
	v_lshlrev_b32_e32 v8, 2, v8
	ds_bpermute_b32 v9, v8, v6
	ds_bpermute_b32 v8, v8, v7
	v_cmp_eq_u32_e32 vcc, 0, v1
	s_waitcnt lgkmcnt(1)
	v_fma_f32 v9, v3, -v10, v9
	s_waitcnt lgkmcnt(0)
	v_fma_f32 v8, v5, -v10, v8
	v_cndmask_b32_e32 v7, v8, v7, vcc
	v_add_u32_e32 v8, -2, v234
	v_cndmask_b32_e32 v6, v9, v6, vcc
	v_cmp_lt_i32_e32 vcc, v8, v242
	s_nop 1
	v_cndmask_b32_e32 v8, v8, v234, vcc
	v_lshlrev_b32_e32 v8, 2, v8
	ds_bpermute_b32 v9, v8, v6
	ds_bpermute_b32 v8, v8, v7
	v_cmp_gt_u32_e32 vcc, 2, v1
	s_waitcnt lgkmcnt(1)
	v_add_f32_e32 v9, v6, v9
	s_waitcnt lgkmcnt(0)
	v_add_f32_e32 v8, v7, v8
	v_cndmask_b32_e32 v7, v8, v7, vcc
	v_add_u32_e32 v8, -4, v234
	v_cndmask_b32_e32 v6, v9, v6, vcc
	v_cmp_lt_i32_e32 vcc, v8, v242
	s_nop 1
	v_cndmask_b32_e32 v8, v8, v234, vcc
	v_lshlrev_b32_e32 v8, 2, v8
	ds_bpermute_b32 v9, v8, v6
	ds_bpermute_b32 v8, v8, v7
	v_cmp_gt_u32_e32 vcc, 4, v1
	s_waitcnt lgkmcnt(1)
	v_add_f32_e32 v9, v6, v9
	s_waitcnt lgkmcnt(0)
	v_add_f32_e32 v8, v7, v8
	v_cndmask_b32_e32 v7, v8, v7, vcc
	v_add_u32_e32 v8, -8, v234
	v_cndmask_b32_e32 v6, v9, v6, vcc
	v_cmp_lt_i32_e32 vcc, v8, v242
	s_nop 1
	v_cndmask_b32_e32 v8, v8, v234, vcc
	v_lshlrev_b32_e32 v8, 2, v8
	ds_bpermute_b32 v9, v8, v6
	ds_bpermute_b32 v8, v8, v7
	v_cmp_gt_u32_e32 vcc, 8, v1
	s_waitcnt lgkmcnt(1)
	v_add_f32_e32 v9, v6, v9
	s_waitcnt lgkmcnt(0)
	v_add_f32_e32 v8, v7, v8
	v_cndmask_b32_e32 v7, v8, v7, vcc
	v_add_u32_e32 v8, -16, v234
	v_cndmask_b32_e32 v6, v9, v6, vcc
	v_cmp_lt_i32_e32 vcc, v8, v242
	s_nop 1
	v_cndmask_b32_e32 v8, v8, v234, vcc
	v_lshlrev_b32_e32 v8, 2, v8
	ds_bpermute_b32 v9, v8, v6
	ds_bpermute_b32 v8, v8, v7
	v_cmp_gt_u32_e32 vcc, 16, v1
	s_waitcnt lgkmcnt(1)
	v_add_f32_e32 v9, v6, v9
	s_waitcnt lgkmcnt(0)
	v_add_f32_e32 v8, v7, v8
	v_cndmask_b32_e32 v7, v8, v7, vcc
	v_subrev_u32_e32 v8, 32, v234
	v_cndmask_b32_e32 v6, v9, v6, vcc
	v_cmp_lt_i32_e32 vcc, v8, v242
	s_nop 1
	v_cndmask_b32_e32 v8, v8, v234, vcc
	v_lshlrev_b32_e32 v8, 2, v8
	ds_bpermute_b32 v9, v8, v6
	ds_bpermute_b32 v8, v8, v7
	v_cmp_gt_u32_e32 vcc, 32, v1
	s_waitcnt lgkmcnt(1)
	v_add_f32_e32 v9, v6, v9
	s_waitcnt lgkmcnt(0)
	v_add_f32_e32 v8, v7, v8
	v_cndmask_b32_e32 v7, v8, v7, vcc
	v_cndmask_b32_e32 v8, v9, v6, vcc
	v_lshl_or_b32 v6, v234, 2, v244
	ds_bpermute_b32 v6, v6, v8
	v_cmp_eq_u32_e32 vcc, 63, v1
	s_waitcnt lgkmcnt(0)
	v_add_f32_e32 v6, v7, v6
	v_lshlrev_b32_e32 v7, 2, v1
	v_lshl_or_b32 v4, v4, 9, v7
	v_add_u32_e32 v4, 0, v4
	ds_write2st64_b32 v4, v3, v5 offset0:204 offset1:205
	ds_write2st64_b32 v4, v8, v6 offset0:220 offset1:221
	s_and_saveexec_b64 s[4:5], vcc
	s_cbranch_execz .LBB0_931
	s_lshl_b32 s7, s47, 4
	s_lshl_b32 s11, s38, 10
	s_or_b32 s7, s7, s11
	v_add_u32_e32 v2, s7, v2
	v_ashrrev_i32_e32 v3, 31, v2
	v_lshl_add_u64 v[2:3], v[2:3], 2, s[34:35]
	global_store_dword v[2:3], v6, off

.LBB0_1205:
	s_ashr_i32 s21, s20, 31
	s_lshl_b64 s[26:27], s[20:21], 17
	s_add_u32 s26, s36, s26
	s_addc_u32 s27, s37, s27
	s_and_b64 s[6:7], s[6:7], exec
	s_cselect_b32 s7, s27, s31
	s_cselect_b32 s6, s26, s30
	s_add_i32 s23, 0, 0x10000
	v_add_u32_e32 v173, s23, v1
	ds_read_b128 v[2:5], v173
	ds_read_b128 v[6:9], v173 offset:1024
	ds_read_b128 v[10:13], v173 offset:2048
	ds_read_b128 v[14:17], v173 offset:3072
	s_add_u32 s46, s28, 0x40080
	s_addc_u32 s47, s29, 0
	s_add_i32 s50, s3, 0xc000
	v_lshl_add_u64 v[50:51], s[46:47], 0, v[138:139]
	s_mov_b32 m0, s50
	s_add_i32 s21, s3, 0xe000
	ds_read_b128 v[18:21], v172
	ds_read_b128 v[22:25], v172 offset:1024
	ds_read_b128 v[26:29], v172 offset:2048
	ds_read_b128 v[30:33], v172 offset:3072
	ds_read_b128 v[34:37], v172 offset:4096
	ds_read_b128 v[38:41], v172 offset:5120
	ds_read_b128 v[42:45], v172 offset:6144
	ds_read_b128 v[46:49], v172 offset:7168
	global_load_lds_dwordx4 v[50:51], off
	v_lshl_add_u64 v[50:51], s[46:47], 0, v[142:143]
	s_mov_b32 m0, s21
	s_nop 0
	global_load_lds_dwordx4 v[50:51], off
	s_waitcnt lgkmcnt(8)
	s_barrier
	s_waitcnt lgkmcnt(0)
	s_waitcnt lgkmcnt(0)
	v_mfma_f32_16x16x32_bf16 v[50:53], v[2:5], v[18:21], 0
	v_mfma_f32_16x16x32_bf16 v[54:57], v[10:13], v[18:21], 0
	v_mfma_f32_16x16x32_bf16 v[58:61], v[2:5], v[26:29], 0
	v_mfma_f32_16x16x32_bf16 v[62:65], v[10:13], v[26:29], 0
	v_mfma_f32_16x16x32_bf16 v[66:69], v[2:5], v[34:37], 0
	v_mfma_f32_16x16x32_bf16 v[70:73], v[10:13], v[34:37], 0
	v_mfma_f32_16x16x32_bf16 v[74:77], v[2:5], v[42:45], 0
	v_mfma_f32_16x16x32_bf16 v[78:81], v[10:13], v[42:45], 0
	v_mfma_f32_16x16x32_bf16 v[50:53], v[6:9], v[22:25], v[50:53]
	v_mfma_f32_16x16x32_bf16 v[54:57], v[14:17], v[22:25], v[54:57]
	v_mfma_f32_16x16x32_bf16 v[58:61], v[6:9], v[30:33], v[58:61]
	v_mfma_f32_16x16x32_bf16 v[62:65], v[14:17], v[30:33], v[62:65]
	v_mfma_f32_16x16x32_bf16 v[66:69], v[6:9], v[38:41], v[66:69]
	v_mfma_f32_16x16x32_bf16 v[70:73], v[14:17], v[38:41], v[70:73]
	v_mfma_f32_16x16x32_bf16 v[74:77], v[6:9], v[46:49], v[74:77]
	v_mfma_f32_16x16x32_bf16 v[78:81], v[14:17], v[46:49], v[78:81]
	s_barrier
	s_add_i32 s48, 0, 0x14000
	v_lshl_add_u64 v[170:171], s[30:31], 0, v[140:141]
	s_mov_b64 s[52:53], 0x100
	s_add_i32 s47, s23, s38
	v_add_u32_e32 v220, s48, v1
	v_lshl_add_u64 v[98:99], v[170:171], 0, s[52:53]
	s_mov_b32 m0, s47
	v_lshl_add_u64 v[186:187], s[30:31], 0, v[144:145]
	s_add_i32 s23, s47, 0x2000
	ds_read_b128 v[82:85], v220
	ds_read_b128 v[86:89], v220 offset:1024
	ds_read_b128 v[90:93], v220 offset:2048
	ds_read_b128 v[94:97], v220 offset:3072
	global_load_lds_dwordx4 v[98:99], off
	v_lshl_add_u64 v[98:99], v[186:187], 0, s[52:53]
	s_mov_b32 m0, s23
	s_nop 0
	global_load_lds_dwordx4 v[98:99], off
	s_barrier
	s_waitcnt lgkmcnt(0)
	s_waitcnt lgkmcnt(0)
	v_mfma_f32_16x16x32_bf16 v[98:101], v[82:85], v[18:21], 0
	v_mfma_f32_16x16x32_bf16 v[18:21], v[90:93], v[18:21], 0
	v_mfma_f32_16x16x32_bf16 v[98:101], v[86:89], v[22:25], v[98:101]
	v_mfma_f32_16x16x32_bf16 v[18:21], v[94:97], v[22:25], v[18:21]
	v_mfma_f32_16x16x32_bf16 v[22:25], v[82:85], v[26:29], 0
	v_mfma_f32_16x16x32_bf16 v[26:29], v[90:93], v[26:29], 0
	v_mfma_f32_16x16x32_bf16 v[22:25], v[86:89], v[30:33], v[22:25]
	v_mfma_f32_16x16x32_bf16 v[26:29], v[94:97], v[30:33], v[26:29]
	v_mfma_f32_16x16x32_bf16 v[30:33], v[82:85], v[34:37], 0
	v_mfma_f32_16x16x32_bf16 v[34:37], v[90:93], v[34:37], 0
	v_mfma_f32_16x16x32_bf16 v[30:33], v[86:89], v[38:41], v[30:33]
	v_mfma_f32_16x16x32_bf16 v[34:37], v[94:97], v[38:41], v[34:37]
	v_mfma_f32_16x16x32_bf16 v[38:41], v[82:85], v[42:45], 0
	v_mfma_f32_16x16x32_bf16 v[42:45], v[90:93], v[42:45], 0
	v_mfma_f32_16x16x32_bf16 v[38:41], v[86:89], v[46:49], v[38:41]
	v_mfma_f32_16x16x32_bf16 v[42:45], v[94:97], v[46:49], v[42:45]
	v_lshl_add_u64 v[188:189], s[28:29], 0, v[138:139]
	s_mov_b32 m0, s3
	v_lshl_add_u64 v[130:131], v[188:189], 0, s[52:53]
	v_lshl_add_u64 v[218:219], s[28:29], 0, v[142:143]
	s_barrier
	ds_read_b128 v[46:49], v172 offset:16384
	ds_read_b128 v[102:105], v172 offset:17408
	ds_read_b128 v[106:109], v172 offset:18432
	ds_read_b128 v[110:113], v172 offset:19456
	ds_read_b128 v[114:117], v172 offset:20480
	ds_read_b128 v[118:121], v172 offset:21504
	ds_read_b128 v[122:125], v172 offset:22528
	ds_read_b128 v[126:129], v172 offset:23552
	global_load_lds_dwordx4 v[130:131], off
	v_lshl_add_u64 v[130:131], v[218:219], 0, s[52:53]
	s_mov_b32 m0, s39
	s_nop 0
	global_load_lds_dwordx4 v[130:131], off
	s_barrier
	s_waitcnt lgkmcnt(0)
	s_waitcnt lgkmcnt(0)
	v_mfma_f32_16x16x32_bf16 v[130:133], v[2:5], v[46:49], 0
	v_mfma_f32_16x16x32_bf16 v[146:149], v[2:5], v[106:109], 0
	v_mfma_f32_16x16x32_bf16 v[154:157], v[2:5], v[114:117], 0
	v_mfma_f32_16x16x32_bf16 v[2:5], v[2:5], v[122:125], 0
	v_mfma_f32_16x16x32_bf16 v[130:133], v[6:9], v[102:105], v[130:133]
	v_mfma_f32_16x16x32_bf16 v[134:137], v[10:13], v[46:49], 0
	v_mfma_f32_16x16x32_bf16 v[146:149], v[6:9], v[110:113], v[146:149]
	v_mfma_f32_16x16x32_bf16 v[150:153], v[10:13], v[106:109], 0
	v_mfma_f32_16x16x32_bf16 v[154:157], v[6:9], v[118:121], v[154:157]
	v_mfma_f32_16x16x32_bf16 v[158:161], v[10:13], v[114:117], 0
	v_mfma_f32_16x16x32_bf16 v[2:5], v[6:9], v[126:129], v[2:5]
	v_mfma_f32_16x16x32_bf16 v[6:9], v[10:13], v[122:125], 0
	v_mfma_f32_16x16x32_bf16 v[134:137], v[14:17], v[102:105], v[134:137]
	v_mfma_f32_16x16x32_bf16 v[150:153], v[14:17], v[110:113], v[150:153]
	v_mfma_f32_16x16x32_bf16 v[158:161], v[14:17], v[118:121], v[158:161]
	v_mfma_f32_16x16x32_bf16 v[6:9], v[14:17], v[126:129], v[6:9]
	s_barrier
	s_add_u32 s52, s30, 0x10100
	s_addc_u32 s53, s31, 0
	s_add_i32 s48, s48, s38
	v_lshl_add_u64 v[10:11], s[52:53], 0, v[140:141]
	s_mov_b32 m0, s48
	s_add_i32 s46, s48, 0x2000
	global_load_lds_dwordx4 v[10:11], off
	v_lshl_add_u64 v[10:11], s[52:53], 0, v[144:145]
	s_mov_b32 m0, s46
	s_nop 0
	global_load_lds_dwordx4 v[10:11], off
	s_waitcnt vmcnt(6)
	s_barrier
	v_mfma_f32_16x16x32_bf16 v[10:13], v[82:85], v[46:49], 0
	v_mfma_f32_16x16x32_bf16 v[14:17], v[90:93], v[46:49], 0
	v_mfma_f32_16x16x32_bf16 v[10:13], v[86:89], v[102:105], v[10:13]
	v_mfma_f32_16x16x32_bf16 v[14:17], v[94:97], v[102:105], v[14:17]
	v_mfma_f32_16x16x32_bf16 v[46:49], v[82:85], v[106:109], 0
	v_mfma_f32_16x16x32_bf16 v[102:105], v[90:93], v[106:109], 0
	v_mfma_f32_16x16x32_bf16 v[106:109], v[82:85], v[114:117], 0
	v_mfma_f32_16x16x32_bf16 v[82:85], v[82:85], v[122:125], 0
	v_mfma_f32_16x16x32_bf16 v[46:49], v[86:89], v[110:113], v[46:49]
	v_mfma_f32_16x16x32_bf16 v[102:105], v[94:97], v[110:113], v[102:105]
	v_mfma_f32_16x16x32_bf16 v[106:109], v[86:89], v[118:121], v[106:109]
	v_mfma_f32_16x16x32_bf16 v[110:113], v[90:93], v[114:117], 0
	v_mfma_f32_16x16x32_bf16 v[82:85], v[86:89], v[126:129], v[82:85]
	v_mfma_f32_16x16x32_bf16 v[86:89], v[90:93], v[122:125], 0
	v_mfma_f32_16x16x32_bf16 v[110:113], v[94:97], v[118:121], v[110:113]
	v_mfma_f32_16x16x32_bf16 v[86:89], v[94:97], v[126:129], v[86:89]
	s_add_i32 s51, 0, 0x18000
	v_add_u32_e32 v232, s51, v1
	s_barrier
	ds_read_b128 v[90:93], v232
	ds_read_b128 v[94:97], v232 offset:1024
	ds_read_b128 v[114:117], v232 offset:2048
	ds_read_b128 v[118:121], v232 offset:3072
	s_add_u32 s52, s28, 0x40100
	s_addc_u32 s53, s29, 0
	s_mov_b32 m0, s40
	v_lshl_add_u64 v[202:203], s[52:53], 0, v[138:139]
	ds_read_b128 v[122:125], v172 offset:32768
	ds_read_b128 v[126:129], v172 offset:33792
	ds_read_b128 v[162:165], v172 offset:34816
	ds_read_b128 v[166:169], v172 offset:35840
	ds_read_b128 v[174:177], v172 offset:36864
	ds_read_b128 v[190:193], v172 offset:37888
	ds_read_b128 v[194:197], v172 offset:38912
	ds_read_b128 v[198:201], v172 offset:39936
	global_load_lds_dwordx4 v[202:203], off
	v_lshl_add_u64 v[202:203], s[52:53], 0, v[142:143]
	s_mov_b32 m0, s41
	s_nop 0
	global_load_lds_dwordx4 v[202:203], off
	s_waitcnt lgkmcnt(8)
	s_barrier
	s_waitcnt lgkmcnt(0)
	s_waitcnt lgkmcnt(0)
	v_mfma_f32_16x16x32_bf16 v[50:53], v[90:93], v[122:125], v[50:53]
	v_mfma_f32_16x16x32_bf16 v[54:57], v[114:117], v[122:125], v[54:57]
	v_mfma_f32_16x16x32_bf16 v[58:61], v[90:93], v[162:165], v[58:61]
	v_mfma_f32_16x16x32_bf16 v[62:65], v[114:117], v[162:165], v[62:65]
	v_mfma_f32_16x16x32_bf16 v[66:69], v[90:93], v[174:177], v[66:69]
	v_mfma_f32_16x16x32_bf16 v[70:73], v[114:117], v[174:177], v[70:73]
	v_mfma_f32_16x16x32_bf16 v[74:77], v[90:93], v[194:197], v[74:77]
	v_mfma_f32_16x16x32_bf16 v[78:81], v[114:117], v[194:197], v[78:81]
	v_mfma_f32_16x16x32_bf16 v[50:53], v[94:97], v[126:129], v[50:53]
	v_mfma_f32_16x16x32_bf16 v[54:57], v[118:121], v[126:129], v[54:57]
	v_mfma_f32_16x16x32_bf16 v[58:61], v[94:97], v[166:169], v[58:61]
	v_mfma_f32_16x16x32_bf16 v[62:65], v[118:121], v[166:169], v[62:65]
	v_mfma_f32_16x16x32_bf16 v[66:69], v[94:97], v[190:193], v[66:69]
	v_mfma_f32_16x16x32_bf16 v[70:73], v[118:121], v[190:193], v[70:73]
	v_mfma_f32_16x16x32_bf16 v[74:77], v[94:97], v[198:201], v[74:77]
	v_mfma_f32_16x16x32_bf16 v[78:81], v[118:121], v[198:201], v[78:81]
	s_barrier
	s_add_i32 s54, 0, 0x1c000
	s_mov_b64 s[52:53], 0x180
	s_add_i32 s51, s51, s38
	v_add_u32_e32 v233, s54, v1
	v_lshl_add_u64 v[170:171], v[170:171], 0, s[52:53]
	s_mov_b32 m0, s51
	s_add_i32 s49, s51, 0x2000
	ds_read_b128 v[202:205], v233
	ds_read_b128 v[206:209], v233 offset:1024
	ds_read_b128 v[210:213], v233 offset:2048
	ds_read_b128 v[214:217], v233 offset:3072
	global_load_lds_dwordx4 v[170:171], off
	v_lshl_add_u64 v[170:171], v[186:187], 0, s[52:53]
	s_mov_b32 m0, s49
	s_nop 0
	global_load_lds_dwordx4 v[170:171], off
	s_barrier
	s_waitcnt lgkmcnt(0)
	s_waitcnt lgkmcnt(0)
	v_mfma_f32_16x16x32_bf16 v[98:101], v[202:205], v[122:125], v[98:101]
	v_mfma_f32_16x16x32_bf16 v[18:21], v[210:213], v[122:125], v[18:21]
	v_mfma_f32_16x16x32_bf16 v[22:25], v[202:205], v[162:165], v[22:25]
	v_mfma_f32_16x16x32_bf16 v[26:29], v[210:213], v[162:165], v[26:29]
	v_mfma_f32_16x16x32_bf16 v[30:33], v[202:205], v[174:177], v[30:33]
	v_mfma_f32_16x16x32_bf16 v[34:37], v[210:213], v[174:177], v[34:37]
	v_mfma_f32_16x16x32_bf16 v[38:41], v[202:205], v[194:197], v[38:41]
	v_mfma_f32_16x16x32_bf16 v[42:45], v[210:213], v[194:197], v[42:45]
	v_mfma_f32_16x16x32_bf16 v[98:101], v[206:209], v[126:129], v[98:101]
	v_mfma_f32_16x16x32_bf16 v[18:21], v[214:217], v[126:129], v[18:21]
	v_mfma_f32_16x16x32_bf16 v[22:25], v[206:209], v[166:169], v[22:25]
	v_mfma_f32_16x16x32_bf16 v[26:29], v[214:217], v[166:169], v[26:29]
	v_mfma_f32_16x16x32_bf16 v[30:33], v[206:209], v[190:193], v[30:33]
	v_mfma_f32_16x16x32_bf16 v[34:37], v[214:217], v[190:193], v[34:37]
	v_mfma_f32_16x16x32_bf16 v[38:41], v[206:209], v[198:201], v[38:41]
	v_mfma_f32_16x16x32_bf16 v[42:45], v[214:217], v[198:201], v[42:45]
	s_mov_b32 m0, s42
	v_lshl_add_u64 v[170:171], v[188:189], 0, s[52:53]
	s_barrier
	ds_read_b128 v[122:125], v172 offset:49152
	ds_read_b128 v[126:129], v172 offset:50176
	ds_read_b128 v[162:165], v172 offset:51200
	ds_read_b128 v[166:169], v172 offset:52224
	ds_read_b128 v[174:177], v172 offset:53248
	ds_read_b128 v[190:193], v172 offset:54272
	ds_read_b128 v[194:197], v172 offset:55296
	ds_read_b128 v[198:201], v172 offset:56320
	global_load_lds_dwordx4 v[170:171], off
	v_lshl_add_u64 v[170:171], v[218:219], 0, s[52:53]
	s_mov_b32 m0, s43
	s_nop 0
	global_load_lds_dwordx4 v[170:171], off
	s_barrier
	s_waitcnt lgkmcnt(0)
	s_waitcnt lgkmcnt(0)
	v_mfma_f32_16x16x32_bf16 v[130:133], v[90:93], v[122:125], v[130:133]
	v_mfma_f32_16x16x32_bf16 v[134:137], v[114:117], v[122:125], v[134:137]
	v_mfma_f32_16x16x32_bf16 v[146:149], v[90:93], v[162:165], v[146:149]
	v_mfma_f32_16x16x32_bf16 v[150:153], v[114:117], v[162:165], v[150:153]
	v_mfma_f32_16x16x32_bf16 v[154:157], v[90:93], v[174:177], v[154:157]
	v_mfma_f32_16x16x32_bf16 v[158:161], v[114:117], v[174:177], v[158:161]
	v_mfma_f32_16x16x32_bf16 v[2:5], v[90:93], v[194:197], v[2:5]
	v_mfma_f32_16x16x32_bf16 v[6:9], v[114:117], v[194:197], v[6:9]
	v_mfma_f32_16x16x32_bf16 v[130:133], v[94:97], v[126:129], v[130:133]
	v_mfma_f32_16x16x32_bf16 v[134:137], v[118:121], v[126:129], v[134:137]
	v_mfma_f32_16x16x32_bf16 v[146:149], v[94:97], v[166:169], v[146:149]
	v_mfma_f32_16x16x32_bf16 v[150:153], v[118:121], v[166:169], v[150:153]
	v_mfma_f32_16x16x32_bf16 v[154:157], v[94:97], v[190:193], v[154:157]
	v_mfma_f32_16x16x32_bf16 v[158:161], v[118:121], v[190:193], v[158:161]
	v_mfma_f32_16x16x32_bf16 v[2:5], v[94:97], v[198:201], v[2:5]
	v_mfma_f32_16x16x32_bf16 v[6:9], v[118:121], v[198:201], v[6:9]
	s_barrier
	s_add_u32 s52, s30, 0x10180
	s_addc_u32 s53, s31, 0
	s_add_i32 s31, s54, s38
	v_lshl_add_u64 v[90:91], s[52:53], 0, v[140:141]
	s_mov_b32 m0, s31
	s_add_i32 s30, s31, 0x2000
	global_load_lds_dwordx4 v[90:91], off
	v_lshl_add_u64 v[90:91], s[52:53], 0, v[144:145]
	s_mov_b32 m0, s30
	s_nop 0
	global_load_lds_dwordx4 v[90:91], off
	s_waitcnt vmcnt(6)
	s_barrier
	v_mfma_f32_16x16x32_bf16 v[10:13], v[202:205], v[122:125], v[10:13]
	v_mfma_f32_16x16x32_bf16 v[14:17], v[210:213], v[122:125], v[14:17]
	v_mfma_f32_16x16x32_bf16 v[46:49], v[202:205], v[162:165], v[46:49]
	v_mfma_f32_16x16x32_bf16 v[90:93], v[210:213], v[162:165], v[102:105]
	v_mfma_f32_16x16x32_bf16 v[94:97], v[202:205], v[174:177], v[106:109]
	v_mfma_f32_16x16x32_bf16 v[102:105], v[210:213], v[174:177], v[110:113]
	v_mfma_f32_16x16x32_bf16 v[82:85], v[202:205], v[194:197], v[82:85]
	v_mfma_f32_16x16x32_bf16 v[86:89], v[210:213], v[194:197], v[86:89]
	v_mfma_f32_16x16x32_bf16 v[10:13], v[206:209], v[126:129], v[10:13]
	v_mfma_f32_16x16x32_bf16 v[14:17], v[214:217], v[126:129], v[14:17]
	v_mfma_f32_16x16x32_bf16 v[46:49], v[206:209], v[166:169], v[46:49]
	v_mfma_f32_16x16x32_bf16 v[90:93], v[214:217], v[166:169], v[90:93]
	v_mfma_f32_16x16x32_bf16 v[94:97], v[206:209], v[190:193], v[94:97]
	v_mfma_f32_16x16x32_bf16 v[102:105], v[214:217], v[190:193], v[102:105]
	v_mfma_f32_16x16x32_bf16 v[82:85], v[206:209], v[198:201], v[82:85]
	v_mfma_f32_16x16x32_bf16 v[86:89], v[214:217], v[198:201], v[86:89]
	s_barrier
	ds_read_b128 v[106:109], v173
	ds_read_b128 v[110:113], v173 offset:1024
	ds_read_b128 v[114:117], v173 offset:2048
	ds_read_b128 v[118:121], v173 offset:3072
	s_add_u32 s28, s28, 0x40180
	s_addc_u32 s29, s29, 0
	s_mov_b32 m0, s50
	v_lshl_add_u64 v[170:171], s[28:29], 0, v[138:139]
	ds_read_b128 v[122:125], v172
	ds_read_b128 v[126:129], v172 offset:1024
	ds_read_b128 v[162:165], v172 offset:2048
	ds_read_b128 v[166:169], v172 offset:3072
	ds_read_b128 v[174:177], v172 offset:4096
	ds_read_b128 v[190:193], v172 offset:5120
	ds_read_b128 v[194:197], v172 offset:6144
	ds_read_b128 v[198:201], v172 offset:7168
	global_load_lds_dwordx4 v[170:171], off
	v_lshl_add_u64 v[170:171], s[28:29], 0, v[142:143]
	s_mov_b32 m0, s21
	s_nop 0
	global_load_lds_dwordx4 v[170:171], off
	s_waitcnt lgkmcnt(8)
	s_barrier
	s_waitcnt lgkmcnt(0)
	s_waitcnt lgkmcnt(0)
	v_mfma_f32_16x16x32_bf16 v[58:61], v[106:109], v[162:165], v[58:61]
	v_mfma_f32_16x16x32_bf16 v[202:205], v[110:113], v[166:169], v[58:61]
	v_mfma_f32_16x16x32_bf16 v[58:61], v[114:117], v[162:165], v[62:65]
	v_mfma_f32_16x16x32_bf16 v[62:65], v[118:121], v[166:169], v[58:61]
	v_mfma_f32_16x16x32_bf16 v[58:61], v[106:109], v[174:177], v[66:69]
	v_mfma_f32_16x16x32_bf16 v[66:69], v[110:113], v[190:193], v[58:61]
	v_mfma_f32_16x16x32_bf16 v[58:61], v[114:117], v[174:177], v[70:73]
	v_mfma_f32_16x16x32_bf16 v[70:73], v[118:121], v[190:193], v[58:61]
	v_mfma_f32_16x16x32_bf16 v[58:61], v[106:109], v[194:197], v[74:77]
	v_mfma_f32_16x16x32_bf16 v[50:53], v[106:109], v[122:125], v[50:53]
	v_mfma_f32_16x16x32_bf16 v[54:57], v[114:117], v[122:125], v[54:57]
	v_mfma_f32_16x16x32_bf16 v[74:77], v[110:113], v[198:201], v[58:61]
	v_mfma_f32_16x16x32_bf16 v[58:61], v[114:117], v[194:197], v[78:81]
	v_mfma_f32_16x16x32_bf16 v[50:53], v[110:113], v[126:129], v[50:53]
	v_mfma_f32_16x16x32_bf16 v[54:57], v[118:121], v[126:129], v[54:57]
	v_mfma_f32_16x16x32_bf16 v[78:81], v[118:121], v[198:201], v[58:61]
	s_barrier
	s_mov_b32 m0, s47
	v_lshl_add_u64 v[170:171], s[6:7], 0, v[140:141]
	s_nop 0
	ds_read_b128 v[58:61], v220
	ds_read_b128 v[206:209], v220 offset:1024
	ds_read_b128 v[210:213], v220 offset:2048
	ds_read_b128 v[214:217], v220 offset:3072
	global_load_lds_dwordx4 v[170:171], off
	v_lshl_add_u64 v[230:231], s[6:7], 0, v[144:145]
	s_mov_b32 m0, s23
	s_nop 0
	global_load_lds_dwordx4 v[230:231], off
	s_barrier
	s_waitcnt lgkmcnt(0)
	s_waitcnt lgkmcnt(0)
	v_mfma_f32_16x16x32_bf16 v[34:37], v[210:213], v[174:177], v[34:37]
	v_mfma_f32_16x16x32_bf16 v[22:25], v[58:61], v[162:165], v[22:25]
	v_mfma_f32_16x16x32_bf16 v[26:29], v[210:213], v[162:165], v[26:29]
	v_mfma_f32_16x16x32_bf16 v[162:165], v[214:217], v[190:193], v[34:37]
	v_mfma_f32_16x16x32_bf16 v[34:37], v[58:61], v[194:197], v[38:41]
	v_mfma_f32_16x16x32_bf16 v[98:101], v[58:61], v[122:125], v[98:101]
	v_mfma_f32_16x16x32_bf16 v[18:21], v[210:213], v[122:125], v[18:21]
	v_mfma_f32_16x16x32_bf16 v[30:33], v[58:61], v[174:177], v[30:33]
	v_mfma_f32_16x16x32_bf16 v[38:41], v[206:209], v[198:201], v[34:37]
	v_mfma_f32_16x16x32_bf16 v[34:37], v[210:213], v[194:197], v[42:45]
	v_mfma_f32_16x16x32_bf16 v[98:101], v[206:209], v[126:129], v[98:101]
	v_mfma_f32_16x16x32_bf16 v[18:21], v[214:217], v[126:129], v[18:21]
	v_mfma_f32_16x16x32_bf16 v[22:25], v[206:209], v[166:169], v[22:25]
	v_mfma_f32_16x16x32_bf16 v[26:29], v[214:217], v[166:169], v[26:29]
	v_mfma_f32_16x16x32_bf16 v[30:33], v[206:209], v[190:193], v[30:33]
	v_mfma_f32_16x16x32_bf16 v[166:169], v[214:217], v[198:201], v[34:37]
	s_mov_b32 m0, s3
	v_lshl_add_u64 v[252:253], s[24:25], 0, v[138:139]
	s_barrier
	ds_read_b128 v[34:37], v172 offset:16384
	ds_read_b128 v[42:45], v172 offset:17408
	ds_read_b128 v[122:125], v172 offset:18432
	ds_read_b128 v[126:129], v172 offset:19456
	ds_read_b128 v[174:177], v172 offset:20480
	ds_read_b128 v[190:193], v172 offset:21504
	ds_read_b128 v[194:197], v172 offset:22528
	ds_read_b128 v[198:201], v172 offset:23552
	global_load_lds_dwordx4 v[252:253], off
	v_lshl_add_u64 v[246:247], s[24:25], 0, v[142:143]
	s_mov_b32 m0, s39
	s_nop 0
	global_load_lds_dwordx4 v[246:247], off
	s_barrier
	s_waitcnt lgkmcnt(0)
	s_waitcnt lgkmcnt(0)
	v_mfma_f32_16x16x32_bf16 v[130:133], v[106:109], v[34:37], v[130:133]
	v_mfma_f32_16x16x32_bf16 v[218:221], v[110:113], v[42:45], v[130:133]
	v_mfma_f32_16x16x32_bf16 v[130:133], v[114:117], v[34:37], v[134:137]
	v_mfma_f32_16x16x32_bf16 v[222:225], v[118:121], v[42:45], v[130:133]
	v_mfma_f32_16x16x32_bf16 v[130:133], v[106:109], v[122:125], v[146:149]
	v_mfma_f32_16x16x32_bf16 v[146:149], v[110:113], v[126:129], v[130:133]
	v_mfma_f32_16x16x32_bf16 v[130:133], v[114:117], v[122:125], v[150:153]
	v_mfma_f32_16x16x32_bf16 v[150:153], v[118:121], v[126:129], v[130:133]
	v_mfma_f32_16x16x32_bf16 v[130:133], v[106:109], v[174:177], v[154:157]
	v_mfma_f32_16x16x32_bf16 v[154:157], v[110:113], v[190:193], v[130:133]
	v_mfma_f32_16x16x32_bf16 v[130:133], v[114:117], v[174:177], v[158:161]
	v_mfma_f32_16x16x32_bf16 v[2:5], v[106:109], v[194:197], v[2:5]
	v_mfma_f32_16x16x32_bf16 v[6:9], v[114:117], v[194:197], v[6:9]
	v_mfma_f32_16x16x32_bf16 v[158:161], v[118:121], v[190:193], v[130:133]
	v_mfma_f32_16x16x32_bf16 v[2:5], v[110:113], v[198:201], v[2:5]
	v_mfma_f32_16x16x32_bf16 v[6:9], v[118:121], v[198:201], v[6:9]
	s_barrier
	s_add_u32 s28, s6, 0x10000
	s_addc_u32 s29, s7, 0
	s_mov_b32 m0, s48
	v_lshl_add_u64 v[106:107], s[28:29], 0, v[140:141]
	global_load_lds_dwordx4 v[106:107], off
	v_lshl_add_u64 v[106:107], s[28:29], 0, v[144:145]
	s_mov_b32 m0, s46
	s_nop 0
	global_load_lds_dwordx4 v[106:107], off
	s_waitcnt vmcnt(6)
	s_barrier
	v_mfma_f32_16x16x32_bf16 v[10:13], v[58:61], v[34:37], v[10:13]
	v_mfma_f32_16x16x32_bf16 v[226:229], v[206:209], v[42:45], v[10:13]
	v_mfma_f32_16x16x32_bf16 v[10:13], v[210:213], v[34:37], v[14:17]
	v_mfma_f32_16x16x32_bf16 v[14:17], v[214:217], v[42:45], v[10:13]
	v_mfma_f32_16x16x32_bf16 v[10:13], v[58:61], v[122:125], v[46:49]
	v_mfma_f32_16x16x32_bf16 v[248:251], v[206:209], v[126:129], v[10:13]
	v_mfma_f32_16x16x32_bf16 v[10:13], v[210:213], v[122:125], v[90:93]
	v_mfma_f32_16x16x32_bf16 v[236:239], v[214:217], v[126:129], v[10:13]
	v_mfma_f32_16x16x32_bf16 v[10:13], v[58:61], v[174:177], v[94:97]
	v_mfma_f32_16x16x32_bf16 v[186:189], v[206:209], v[190:193], v[10:13]
	v_mfma_f32_16x16x32_bf16 v[10:13], v[210:213], v[174:177], v[102:105]
	v_mfma_f32_16x16x32_bf16 v[174:177], v[214:217], v[190:193], v[10:13]
	v_mfma_f32_16x16x32_bf16 v[10:13], v[58:61], v[194:197], v[82:85]
	v_mfma_f32_16x16x32_bf16 v[190:193], v[206:209], v[198:201], v[10:13]
	v_mfma_f32_16x16x32_bf16 v[10:13], v[210:213], v[194:197], v[86:89]
	v_mfma_f32_16x16x32_bf16 v[194:197], v[214:217], v[198:201], v[10:13]
	s_barrier
	ds_read_b128 v[86:89], v232
	ds_read_b128 v[94:97], v232 offset:1024
	ds_read_b128 v[102:105], v232 offset:2048
	ds_read_b128 v[198:201], v232 offset:3072
	s_add_u32 s28, s24, 0x40000
	s_addc_u32 s29, s25, 0
	s_mov_b32 m0, s40
	v_lshl_add_u64 v[34:35], s[28:29], 0, v[138:139]
	ds_read_b128 v[10:13], v172 offset:32768
	ds_read_b128 v[46:49], v172 offset:33792
	ds_read_b128 v[82:85], v172 offset:34816
	ds_read_b128 v[90:93], v172 offset:35840
	ds_read_b128 v[110:113], v172 offset:36864
	ds_read_b128 v[206:209], v172 offset:37888
	ds_read_b128 v[210:213], v172 offset:38912
	ds_read_b128 v[214:217], v172 offset:39936
	global_load_lds_dwordx4 v[34:35], off
	v_lshl_add_u64 v[34:35], s[28:29], 0, v[142:143]
	s_mov_b32 m0, s41
	s_nop 0
	global_load_lds_dwordx4 v[34:35], off
	s_waitcnt lgkmcnt(8)
	s_barrier
	s_waitcnt lgkmcnt(0)
	s_waitcnt lgkmcnt(0)
	v_mfma_f32_16x16x32_bf16 v[34:37], v[86:89], v[10:13], v[50:53]
	v_mfma_f32_16x16x32_bf16 v[130:133], v[94:97], v[46:49], v[34:37]
	v_mfma_f32_16x16x32_bf16 v[34:37], v[102:105], v[10:13], v[54:57]
	v_mfma_f32_16x16x32_bf16 v[58:61], v[198:201], v[46:49], v[34:37]
	v_mfma_f32_16x16x32_bf16 v[34:37], v[86:89], v[82:85], v[202:205]
	v_mfma_f32_16x16x32_bf16 v[122:125], v[94:97], v[90:93], v[34:37]
	v_mfma_f32_16x16x32_bf16 v[34:37], v[102:105], v[82:85], v[62:65]
	v_mfma_f32_16x16x32_bf16 v[50:53], v[198:201], v[90:93], v[34:37]
	v_mfma_f32_16x16x32_bf16 v[34:37], v[86:89], v[110:113], v[66:69]
	v_mfma_f32_16x16x32_bf16 v[114:117], v[94:97], v[206:209], v[34:37]
	v_mfma_f32_16x16x32_bf16 v[34:37], v[102:105], v[110:113], v[70:73]
	v_mfma_f32_16x16x32_bf16 v[42:45], v[198:201], v[206:209], v[34:37]
	v_mfma_f32_16x16x32_bf16 v[34:37], v[86:89], v[210:213], v[74:77]
	v_mfma_f32_16x16x32_bf16 v[106:109], v[94:97], v[214:217], v[34:37]
	v_mfma_f32_16x16x32_bf16 v[34:37], v[102:105], v[210:213], v[78:81]
	v_mfma_f32_16x16x32_bf16 v[34:37], v[198:201], v[214:217], v[34:37]
	s_barrier
	s_mov_b32 m0, s51
	v_lshl_add_u64 v[54:55], v[170:171], 0, s[0:1]
	ds_read_b128 v[70:73], v233
	ds_read_b128 v[74:77], v233 offset:1024
	ds_read_b128 v[78:81], v233 offset:2048
	ds_read_b128 v[202:205], v233 offset:3072
	global_load_lds_dwordx4 v[54:55], off
	v_lshl_add_u64 v[54:55], v[230:231], 0, s[0:1]
	s_mov_b32 m0, s49
	s_nop 0
	global_load_lds_dwordx4 v[54:55], off
	s_barrier
	s_waitcnt lgkmcnt(0)
	s_waitcnt lgkmcnt(0)
	v_mfma_f32_16x16x32_bf16 v[54:57], v[70:73], v[10:13], v[98:101]
	v_mfma_f32_16x16x32_bf16 v[10:13], v[78:81], v[10:13], v[18:21]
	v_mfma_f32_16x16x32_bf16 v[62:65], v[202:205], v[46:49], v[10:13]
	v_mfma_f32_16x16x32_bf16 v[10:13], v[70:73], v[82:85], v[22:25]
	v_mfma_f32_16x16x32_bf16 v[126:129], v[74:77], v[90:93], v[10:13]
	v_mfma_f32_16x16x32_bf16 v[10:13], v[78:81], v[82:85], v[26:29]
	v_mfma_f32_16x16x32_bf16 v[134:137], v[74:77], v[46:49], v[54:57]
	v_mfma_f32_16x16x32_bf16 v[54:57], v[202:205], v[90:93], v[10:13]
	v_mfma_f32_16x16x32_bf16 v[10:13], v[70:73], v[110:113], v[30:33]
	v_mfma_f32_16x16x32_bf16 v[118:121], v[74:77], v[206:209], v[10:13]
	v_mfma_f32_16x16x32_bf16 v[10:13], v[78:81], v[110:113], v[162:165]
	v_mfma_f32_16x16x32_bf16 v[46:49], v[202:205], v[206:209], v[10:13]
	v_mfma_f32_16x16x32_bf16 v[10:13], v[70:73], v[210:213], v[38:41]
	v_mfma_f32_16x16x32_bf16 v[110:113], v[74:77], v[214:217], v[10:13]
	v_mfma_f32_16x16x32_bf16 v[10:13], v[78:81], v[210:213], v[166:169]
	v_mfma_f32_16x16x32_bf16 v[38:41], v[202:205], v[214:217], v[10:13]
	s_mov_b32 m0, s42
	s_nop 4
	v_lshl_add_u64 v[10:11], v[252:253], 0, s[0:1]
	s_barrier
	ds_read_b128 v[22:25], v172 offset:49152
	ds_read_b128 v[30:33], v172 offset:50176
	ds_read_b128 v[162:165], v172 offset:51200
	ds_read_b128 v[166:169], v172 offset:52224
	ds_read_b128 v[206:209], v172 offset:53248
	ds_read_b128 v[210:213], v172 offset:54272
	ds_read_b128 v[214:217], v172 offset:55296
	ds_read_b128 v[230:233], v172 offset:56320
	global_load_lds_dwordx4 v[10:11], off
	v_lshl_add_u64 v[10:11], v[246:247], 0, s[0:1]
	s_mov_b32 m0, s43
	s_nop 0
	global_load_lds_dwordx4 v[10:11], off
	s_barrier
	s_waitcnt lgkmcnt(0)
	s_waitcnt lgkmcnt(0)
	v_mfma_f32_16x16x32_bf16 v[10:13], v[86:89], v[22:25], v[218:221]
	v_mfma_f32_16x16x32_bf16 v[98:101], v[94:97], v[30:33], v[10:13]
	v_mfma_f32_16x16x32_bf16 v[10:13], v[102:105], v[22:25], v[222:225]
	v_mfma_f32_16x16x32_bf16 v[26:29], v[198:201], v[30:33], v[10:13]
	v_mfma_f32_16x16x32_bf16 v[10:13], v[86:89], v[162:165], v[146:149]
	v_mfma_f32_16x16x32_bf16 v[90:93], v[94:97], v[166:169], v[10:13]
	v_mfma_f32_16x16x32_bf16 v[10:13], v[102:105], v[162:165], v[150:153]
	v_mfma_f32_16x16x32_bf16 v[18:21], v[198:201], v[166:169], v[10:13]
	v_mfma_f32_16x16x32_bf16 v[10:13], v[86:89], v[206:209], v[154:157]
	v_mfma_f32_16x16x32_bf16 v[2:5], v[86:89], v[214:217], v[2:5]
	v_mfma_f32_16x16x32_bf16 v[82:85], v[94:97], v[210:213], v[10:13]
	v_mfma_f32_16x16x32_bf16 v[10:13], v[102:105], v[206:209], v[158:161]
	v_mfma_f32_16x16x32_bf16 v[66:69], v[94:97], v[230:233], v[2:5]
	v_mfma_f32_16x16x32_bf16 v[2:5], v[102:105], v[214:217], v[6:9]
	v_mfma_f32_16x16x32_bf16 v[10:13], v[198:201], v[210:213], v[10:13]
	v_mfma_f32_16x16x32_bf16 v[2:5], v[198:201], v[230:233], v[2:5]
	s_barrier
	s_add_u32 s6, s6, 0x10080
	s_addc_u32 s7, s7, 0
	s_mov_b32 m0, s31
	v_lshl_add_u64 v[6:7], s[6:7], 0, v[140:141]
	global_load_lds_dwordx4 v[6:7], off
	v_lshl_add_u64 v[6:7], s[6:7], 0, v[144:145]
	s_mov_b32 m0, s30
	s_nop 0
	global_load_lds_dwordx4 v[6:7], off
	s_waitcnt vmcnt(6)
	s_barrier
	v_mfma_f32_16x16x32_bf16 v[6:9], v[70:73], v[22:25], v[226:229]
	v_mfma_f32_16x16x32_bf16 v[102:105], v[74:77], v[30:33], v[6:9]
	v_mfma_f32_16x16x32_bf16 v[6:9], v[78:81], v[22:25], v[14:17]
	v_mfma_f32_16x16x32_bf16 v[30:33], v[202:205], v[30:33], v[6:9]
	v_mfma_f32_16x16x32_bf16 v[6:9], v[70:73], v[162:165], v[248:251]
	v_mfma_f32_16x16x32_bf16 v[94:97], v[74:77], v[166:169], v[6:9]
	v_mfma_f32_16x16x32_bf16 v[6:9], v[78:81], v[162:165], v[236:239]
	v_mfma_f32_16x16x32_bf16 v[22:25], v[202:205], v[166:169], v[6:9]
	v_mfma_f32_16x16x32_bf16 v[6:9], v[70:73], v[206:209], v[186:189]
	v_mfma_f32_16x16x32_bf16 v[86:89], v[74:77], v[210:213], v[6:9]
	v_mfma_f32_16x16x32_bf16 v[6:9], v[78:81], v[206:209], v[174:177]
	v_mfma_f32_16x16x32_bf16 v[14:17], v[202:205], v[210:213], v[6:9]
	v_mfma_f32_16x16x32_bf16 v[6:9], v[70:73], v[214:217], v[190:193]
	v_mfma_f32_16x16x32_bf16 v[70:73], v[74:77], v[230:233], v[6:9]
	v_mfma_f32_16x16x32_bf16 v[6:9], v[78:81], v[214:217], v[194:197]
	v_mfma_f32_16x16x32_bf16 v[6:9], v[202:205], v[230:233], v[6:9]
	v_mov_b32_e32 v74, v178
	s_barrier
	s_add_i32 s45, s45, s34
	v_ashrrev_i32_e32 v75, 2, v74
	v_and_b32_e32 v75, 0xffffffc0, v75
	v_lshl_add_u32 v75, s2, 8, v75
	v_and_or_b32 v148, v74, 15, v75
	v_lshrrev_b32_e32 v74, 1, v74
	v_and_b32_e32 v74, 0x78, v74
	v_lshl_or_b32 v150, s33, 7, v74
	v_ashrrev_i32_e32 v151, 31, v150
	v_lshlrev_b64 v[146:147], 2, v[150:151]
	v_lshl_add_u64 v[154:155], s[10:11], 0, v[146:147]
	global_load_dwordx4 v[158:161], v[154:155], off
	v_lshl_add_u64 v[152:153], s[16:17], 0, v[146:147]
	v_lshl_add_u64 v[156:157], s[8:9], 0, v[146:147]
	global_load_dwordx4 v[78:81], v[152:153], off
	global_load_dwordx4 v[74:77], v[156:157], off
	v_mov_b32_e32 v166, v148
	s_mov_b32 s2, 0xc1000000
	v_ashrrev_i32_e32 v167, 31, v166
	global_load_dwordx4 v[236:239], v[152:153], off offset:16
	global_load_dwordx4 v[246:249], v[156:157], off offset:16
	global_load_dwordx4 v[250:253], v[154:155], off offset:16
	v_lshlrev_b64 v[146:147], 11, v[166:167]
	v_lshl_add_u64 v[168:169], s[14:15], 0, v[146:147]
	v_lshlrev_b64 v[146:147], 1, v[150:151]
	v_lshl_add_u64 v[168:169], v[168:169], 0, v[146:147]
	v_mov_b32_e32 v230, v168
	v_mov_b32_e32 v231, v169
	v_mov_b32_e32 v232, 0x8000
	v_mov_b32_e32 v233, 0
	global_load_dwordx2 v[174:175], v[230:231], off
	global_load_dwordx2 v[202:203], v[230:231], off offset:8
	v_lshl_add_u64 v[230:231], v[230:231], 0, v[232:233]
	global_load_dwordx2 v[176:177], v[230:231], off
	global_load_dwordx2 v[204:205], v[230:231], off offset:8
	v_lshl_add_u64 v[230:231], v[230:231], 0, v[232:233]
	global_load_dwordx2 v[190:191], v[230:231], off
	global_load_dwordx2 v[206:207], v[230:231], off offset:8
	v_lshl_add_u64 v[230:231], v[230:231], 0, v[232:233]
	global_load_dwordx2 v[192:193], v[230:231], off
	global_load_dwordx2 v[208:209], v[230:231], off offset:8
	v_mov_b32_e32 v232, 0x28000
	v_lshl_add_u64 v[230:231], v[230:231], 0, v[232:233]
	v_mov_b32_e32 v232, 0x8000
	global_load_dwordx2 v[194:195], v[230:231], off
	global_load_dwordx2 v[210:211], v[230:231], off offset:8
	v_lshl_add_u64 v[230:231], v[230:231], 0, v[232:233]
	global_load_dwordx2 v[196:197], v[230:231], off
	global_load_dwordx2 v[212:213], v[230:231], off offset:8
	v_lshl_add_u64 v[230:231], v[230:231], 0, v[232:233]
	global_load_dwordx2 v[198:199], v[230:231], off
	global_load_dwordx2 v[214:215], v[230:231], off offset:8
	v_lshl_add_u64 v[230:231], v[230:231], 0, v[232:233]
	global_load_dwordx2 v[200:201], v[230:231], off
	global_load_dwordx2 v[216:217], v[230:231], off offset:8
	s_mov_b32 s33, s20
	s_mov_b64 s[30:31], s[26:27]
	s_mov_b64 s[28:29], s[24:25]
	s_waitcnt vmcnt(19)
	v_max_f32_e64 v146, -v158, -v158
	v_max_f32_e32 v162, 0, v146
	v_mul_f32_e64 v146, |v158|, s72
	v_exp_f32_e32 v146, v146
	v_add_f32_e32 v130, v130, v78
	v_add_f32_e32 v131, v131, v79
	v_mul_f32_e32 v130, 0xbfb8aa3b, v130
	v_add_f32_e32 v146, 1.0, v146
	v_cmp_gt_f32_e32 vcc, s71, v146
	v_mul_f32_e32 v131, 0xbfb8aa3b, v131
	v_exp_f32_e32 v130, v130
	v_cndmask_b32_e64 v147, 0, 32, vcc
	v_ldexp_f32 v146, v146, v147
	v_log_f32_e32 v146, v146
	v_exp_f32_e32 v131, v131
	v_add_f32_e32 v130, 1.0, v130
	v_rcp_f32_e32 v170, v130
	v_mul_f32_e32 v147, 0x3f317217, v146
	v_fma_f32 v147, v146, s73, -v147
	v_fmac_f32_e32 v147, 0x3377d1cf, v146
	v_fmac_f32_e32 v147, 0x3f317217, v146
	v_cmp_lt_f32_e64 s[6:7], |v146|, s74
	v_add_f32_e32 v131, 1.0, v131
	v_rcp_f32_e32 v171, v131
	v_cndmask_b32_e64 v146, v146, v147, s[6:7]
	v_cndmask_b32_e32 v147, 0, v243, vcc
	v_sub_f32_e32 v164, v146, v147
	v_max_f32_e64 v146, -v159, -v159
	v_max_f32_e32 v163, 0, v146
	v_mul_f32_e64 v146, |v159|, s72
	v_exp_f32_e32 v146, v146
	v_add_f32_e32 v130, v134, v74
	v_add_f32_e32 v131, v135, v75
	v_mul_f32_e32 v130, 0xbfb8aa3b, v130
	v_add_f32_e32 v146, 1.0, v146
	v_cmp_gt_f32_e32 vcc, s71, v146
	v_mul_f32_e32 v131, 0xbfb8aa3b, v131
	v_exp_f32_e32 v130, v130
	v_cndmask_b32_e64 v147, 0, 32, vcc
	v_ldexp_f32 v146, v146, v147
	v_log_f32_e32 v146, v146
	v_exp_f32_e32 v131, v131
	v_add_f32_e32 v130, 1.0, v130
	v_rcp_f32_e32 v130, v130
	v_mul_f32_e32 v147, 0x3f317217, v146
	v_fma_f32 v147, v146, s73, -v147
	v_fmac_f32_e32 v147, 0x3377d1cf, v146
	v_fmac_f32_e32 v147, 0x3f317217, v146
	v_cmp_lt_f32_e64 s[6:7], |v146|, s74
	v_add_f32_e32 v131, 1.0, v131
	v_rcp_f32_e32 v131, v131
	v_cndmask_b32_e64 v146, v146, v147, s[6:7]
	v_cndmask_b32_e32 v147, 0, v243, vcc
	v_sub_f32_e32 v165, v146, v147
	v_max_f32_e64 v146, -v160, -v160
	v_max_f32_e32 v158, 0, v146
	v_mul_f32_e64 v146, |v160|, s72
	v_exp_f32_e32 v146, v146
	v_pk_add_f32 v[134:135], v[162:163], v[164:165]
	v_add_f32_e32 v122, v122, v78
	v_pk_mul_f32 v[134:135], v[134:135], s[2:3] op_sel_hi:[1,0]
	v_add_f32_e32 v146, 1.0, v146
	v_cmp_gt_f32_e32 vcc, s71, v146
	v_pk_mul_f32 v[162:163], v[170:171], v[134:135]
	v_add_f32_e32 v123, v123, v79
	v_cndmask_b32_e64 v147, 0, 32, vcc
	v_ldexp_f32 v146, v146, v147
	v_log_f32_e32 v146, v146
	v_add_f32_e32 v149, v162, v162
	v_mul_f32_e32 v149, 0x3fb8aa3b, v149
	v_exp_f32_e32 v149, v149
	v_mul_f32_e32 v147, 0x3f317217, v146
	v_fma_f32 v147, v146, s73, -v147
	v_fmac_f32_e32 v147, 0x3377d1cf, v146
	v_fmac_f32_e32 v147, 0x3f317217, v146
	v_cmp_lt_f32_e64 s[6:7], |v146|, s74
	v_sub_f32_e32 v149, 1.0, v149
	v_max_f32_e32 v149, 0, v149
	v_cndmask_b32_e64 v146, v146, v147, s[6:7]
	v_cndmask_b32_e32 v147, 0, v243, vcc
	v_sub_f32_e32 v160, v146, v147
	v_max_f32_e64 v146, -v161, -v161
	v_max_f32_e32 v159, 0, v146
	v_mul_f32_e64 v146, |v161|, s72
	v_exp_f32_e32 v146, v146
	v_sqrt_f32_e32 v164, v149
	v_add_f32_e32 v149, v163, v163
	v_mul_f32_e32 v149, 0x3fb8aa3b, v149
	v_add_f32_e32 v146, 1.0, v146
	v_cmp_gt_f32_e32 vcc, s71, v146
	v_exp_f32_e32 v149, v149
	v_mul_f32_e32 v122, 0xbfb8aa3b, v122
	v_cndmask_b32_e64 v147, 0, 32, vcc
	v_ldexp_f32 v146, v146, v147
	v_log_f32_e32 v146, v146
	v_sub_f32_e32 v149, 1.0, v149
	v_max_f32_e32 v149, 0, v149
	v_sqrt_f32_e32 v165, v149
	v_mul_f32_e32 v147, 0x3f317217, v146
	v_fma_f32 v147, v146, s73, -v147
	v_fmac_f32_e32 v147, 0x3377d1cf, v146
	v_fmac_f32_e32 v147, 0x3f317217, v146
	v_cmp_lt_f32_e64 s[6:7], |v146|, s74
	v_pk_mul_f32 v[130:131], v[130:131], v[164:165]
	v_mul_f32_e32 v123, 0xbfb8aa3b, v123
	v_cndmask_b32_e64 v146, v146, v147, s[6:7]
	v_cndmask_b32_e32 v147, 0, v243, vcc
	v_sub_f32_e32 v161, v146, v147
	v_exp_f32_e32 v122, v122
	v_exp_f32_e32 v123, v123
	v_add_f32_e32 v126, v126, v74
	v_add_f32_e32 v127, v127, v75
	v_add_f32_e32 v122, 1.0, v122
	v_add_f32_e32 v123, 1.0, v123
	v_rcp_f32_e32 v122, v122
	v_rcp_f32_e32 v123, v123
	v_mul_f32_e32 v126, 0xbfb8aa3b, v126
	v_mul_f32_e32 v127, 0xbfb8aa3b, v127
	v_exp_f32_e32 v126, v126
	v_exp_f32_e32 v127, v127
	v_add_f32_e32 v114, v114, v78
	v_add_f32_e32 v115, v115, v79
	v_add_f32_e32 v126, 1.0, v126
	v_add_f32_e32 v127, 1.0, v127
	v_rcp_f32_e32 v126, v126
	v_rcp_f32_e32 v127, v127
	v_mul_f32_e32 v114, 0xbfb8aa3b, v114
	v_mul_f32_e32 v115, 0xbfb8aa3b, v115
	v_exp_f32_e32 v114, v114
	v_exp_f32_e32 v115, v115
	v_add_f32_e32 v118, v118, v74
	v_add_f32_e32 v119, v119, v75
	v_add_f32_e32 v114, 1.0, v114
	v_add_f32_e32 v115, 1.0, v115
	v_rcp_f32_e32 v114, v114
	v_rcp_f32_e32 v115, v115
	v_mul_f32_e32 v118, 0xbfb8aa3b, v118
	v_mul_f32_e32 v119, 0xbfb8aa3b, v119
	v_exp_f32_e32 v118, v118
	v_exp_f32_e32 v119, v119
	v_add_f32_e32 v106, v106, v78
	v_add_f32_e32 v107, v107, v79
	v_add_f32_e32 v118, 1.0, v118
	v_add_f32_e32 v119, 1.0, v119
	v_rcp_f32_e32 v118, v118
	v_rcp_f32_e32 v119, v119
	v_mul_f32_e32 v106, 0xbfb8aa3b, v106
	v_mul_f32_e32 v107, 0xbfb8aa3b, v107
	v_exp_f32_e32 v106, v106
	v_exp_f32_e32 v107, v107
	v_add_f32_e32 v110, v110, v74
	v_add_f32_e32 v111, v111, v75
	v_add_f32_e32 v106, 1.0, v106
	v_add_f32_e32 v107, 1.0, v107
	v_rcp_f32_e32 v106, v106
	v_rcp_f32_e32 v107, v107
	v_mul_f32_e32 v110, 0xbfb8aa3b, v110
	v_mul_f32_e32 v111, 0xbfb8aa3b, v111
	v_exp_f32_e32 v110, v110
	v_exp_f32_e32 v111, v111
	v_add_f32_e32 v98, v98, v78
	v_add_f32_e32 v99, v99, v79
	v_add_f32_e32 v110, 1.0, v110
	v_add_f32_e32 v111, 1.0, v111
	v_rcp_f32_e32 v110, v110
	v_rcp_f32_e32 v111, v111
	v_mul_f32_e32 v98, 0xbfb8aa3b, v98
	v_mul_f32_e32 v99, 0xbfb8aa3b, v99
	v_exp_f32_e32 v98, v98
	v_exp_f32_e32 v99, v99
	v_add_f32_e32 v102, v102, v74
	v_add_f32_e32 v103, v103, v75
	v_add_f32_e32 v98, 1.0, v98
	v_add_f32_e32 v99, 1.0, v99
	v_rcp_f32_e32 v98, v98
	v_rcp_f32_e32 v99, v99
	v_mul_f32_e32 v102, 0xbfb8aa3b, v102
	v_mul_f32_e32 v103, 0xbfb8aa3b, v103
	v_exp_f32_e32 v102, v102
	v_exp_f32_e32 v103, v103
	v_add_f32_e32 v90, v90, v78
	v_add_f32_e32 v91, v91, v79
	v_add_f32_e32 v102, 1.0, v102
	v_add_f32_e32 v103, 1.0, v103
	v_rcp_f32_e32 v102, v102
	v_rcp_f32_e32 v103, v103
	v_mul_f32_e32 v90, 0xbfb8aa3b, v90
	s_waitcnt vmcnt(0)
	v_mov_b32_e32 v168, v174
	v_mov_b32_e32 v169, v175
	v_lshlrev_b32_e32 v170, 16, v168
	v_and_b32_e32 v171, 0xffff0000, v168
	v_pk_mul_f32 v[164:165], v[130:131], v[170:171]
	v_add_f32_e32 v131, v136, v76
	v_mul_f32_e32 v131, 0xbfb8aa3b, v131
	v_exp_f32_e32 v131, v131
	v_add_f32_e32 v130, v132, v80
	v_mul_f32_e32 v130, 0xbfb8aa3b, v130
	v_exp_f32_e32 v130, v130
	v_add_f32_e32 v131, 1.0, v131
	v_rcp_f32_e32 v136, v131
	v_add_f32_e32 v131, v133, v81
	v_mul_f32_e32 v131, 0xbfb8aa3b, v131
	v_exp_f32_e32 v131, v131
	v_add_f32_e32 v132, v137, v77
	v_mul_f32_e32 v132, 0xbfb8aa3b, v132
	v_exp_f32_e32 v132, v132
	v_add_f32_e32 v130, 1.0, v130
	v_add_f32_e32 v131, 1.0, v131
	v_rcp_f32_e32 v130, v130
	v_rcp_f32_e32 v131, v131
	v_add_f32_e32 v132, 1.0, v132
	v_rcp_f32_e32 v137, v132
	v_pk_add_f32 v[132:133], v[158:159], v[160:161]
	v_lshlrev_b32_e32 v160, 16, v169
	v_pk_mul_f32 v[132:133], v[132:133], s[2:3] op_sel_hi:[1,0]
	v_and_b32_e32 v161, 0xffff0000, v169
	v_pk_mul_f32 v[130:131], v[130:131], v[132:133]
	v_mul_f32_e32 v91, 0xbfb8aa3b, v91
	v_add_f32_e32 v149, v130, v130
	v_mul_f32_e32 v149, 0x3fb8aa3b, v149
	v_exp_f32_e32 v149, v149
	v_exp_f32_e32 v90, v90
	v_exp_f32_e32 v91, v91
	v_add_f32_e32 v94, v94, v74
	v_sub_f32_e32 v149, 1.0, v149
	v_max_f32_e32 v149, 0, v149
	v_sqrt_f32_e32 v158, v149
	v_add_f32_e32 v149, v131, v131
	v_mul_f32_e32 v149, 0x3fb8aa3b, v149
	v_exp_f32_e32 v149, v149
	v_add_f32_e32 v90, 1.0, v90
	v_add_f32_e32 v91, 1.0, v91
	v_rcp_f32_e32 v90, v90
	v_sub_f32_e32 v149, 1.0, v149
	v_max_f32_e32 v149, 0, v149
	v_sqrt_f32_e32 v159, v149
	v_rcp_f32_e32 v91, v91
	v_add_f32_e32 v95, v95, v75
	v_mul_f32_e32 v94, 0xbfb8aa3b, v94
	v_pk_mul_f32 v[136:137], v[136:137], v[158:159]
	v_mul_f32_e32 v95, 0xbfb8aa3b, v95
	v_pk_mul_f32 v[158:159], v[136:137], v[160:161]
	v_cvt_pk_bf16_f32 v161, v130, v131
	v_mov_b64_e32 v[130:131], s[18:19]
	v_cvt_pk_bf16_f32 v160, v162, v163
	v_mad_i64_i32 v[162:163], s[6:7], v166, s84, v[130:131]
	v_lshl_add_u64 v[162:163], v[162:163], 0, v[146:147]
	v_add_co_u32_e32 v162, vcc, s69, v162
	v_add_u32_e32 v136, 16, v166
	s_nop 0
	v_addc_co_u32_e32 v163, vcc, 0, v163, vcc
	v_mov_b32_e32 v220, v160
	v_mov_b32_e32 v221, v161
	v_cvt_pk_bf16_f32 v160, v164, v165
	v_cvt_pk_bf16_f32 v161, v158, v159
	v_mov_b32_e32 v224, v160
	v_mov_b32_e32 v225, v161
	v_pk_mul_f32 v[160:161], v[122:123], v[134:135]
	v_ashrrev_i32_e32 v137, 31, v136
	v_lshlrev_b64 v[158:159], 11, v[136:137]
	v_lshl_add_u64 v[158:159], s[14:15], 0, v[158:159]
	v_lshl_add_u64 v[158:159], v[158:159], 0, v[146:147]
	s_nop 0
	v_add_f32_e32 v122, v160, v160
	v_add_f32_e32 v123, v161, v161
	v_mul_f32_e32 v122, 0x3fb8aa3b, v122
	v_mul_f32_e32 v123, 0x3fb8aa3b, v123
	v_exp_f32_e32 v122, v122
	v_exp_f32_e32 v123, v123
	v_exp_f32_e32 v94, v94
	v_exp_f32_e32 v95, v95
	v_sub_f32_e32 v122, 1.0, v122
	v_sub_f32_e32 v123, 1.0, v123
	v_max_f32_e32 v122, 0, v122
	v_max_f32_e32 v123, 0, v123
	v_sqrt_f32_e32 v122, v122
	v_sqrt_f32_e32 v123, v123
	v_add_f32_e32 v94, 1.0, v94
	v_add_f32_e32 v95, 1.0, v95
	v_rcp_f32_e32 v94, v94
	v_pk_mul_f32 v[122:123], v[126:127], v[122:123]
	v_rcp_f32_e32 v95, v95
	v_add_f32_e32 v82, v82, v78
	v_add_f32_e32 v83, v83, v79
	v_mul_f32_e32 v82, 0xbfb8aa3b, v82
	v_mul_f32_e32 v83, 0xbfb8aa3b, v83
	v_exp_f32_e32 v82, v82
	v_exp_f32_e32 v83, v83
	v_add_f32_e32 v86, v86, v74
	v_add_f32_e32 v87, v87, v75
	v_add_f32_e32 v82, 1.0, v82
	v_add_f32_e32 v83, 1.0, v83
	v_rcp_f32_e32 v82, v82
	v_rcp_f32_e32 v83, v83
	v_mul_f32_e32 v86, 0xbfb8aa3b, v86
	v_mul_f32_e32 v87, 0xbfb8aa3b, v87
	v_exp_f32_e32 v86, v86
	v_exp_f32_e32 v87, v87
	v_add_f32_e32 v66, v66, v78
	v_add_f32_e32 v67, v67, v79
	v_add_f32_e32 v86, 1.0, v86
	v_add_f32_e32 v87, 1.0, v87
	v_rcp_f32_e32 v86, v86
	v_rcp_f32_e32 v87, v87
	v_mul_f32_e32 v66, 0xbfb8aa3b, v66
	v_mul_f32_e32 v67, 0xbfb8aa3b, v67
	v_exp_f32_e32 v66, v66
	v_exp_f32_e32 v67, v67
	v_add_f32_e32 v70, v70, v74
	v_add_f32_e32 v71, v71, v75
	v_add_f32_e32 v66, 1.0, v66
	v_add_f32_e32 v67, 1.0, v67
	v_rcp_f32_e32 v66, v66
	v_rcp_f32_e32 v67, v67
	v_add_f32_e32 v68, v68, v80
	v_add_f32_e32 v69, v69, v81
	v_mul_f32_e32 v68, 0xbfb8aa3b, v68
	v_pk_mul_f32 v[66:67], v[66:67], v[134:135]
	v_mul_f32_e32 v69, 0xbfb8aa3b, v69
	v_add_f32_e32 v74, v66, v66
	v_add_f32_e32 v75, v67, v67
	v_mul_f32_e32 v74, 0x3fb8aa3b, v74
	v_mul_f32_e32 v75, 0x3fb8aa3b, v75
	v_mul_f32_e32 v70, 0xbfb8aa3b, v70
	v_mul_f32_e32 v71, 0xbfb8aa3b, v71
	v_exp_f32_e32 v74, v74
	v_exp_f32_e32 v75, v75
	v_exp_f32_e32 v68, v68
	v_exp_f32_e32 v69, v69
	v_exp_f32_e32 v70, v70
	v_exp_f32_e32 v71, v71
	v_sub_f32_e32 v74, 1.0, v74
	v_sub_f32_e32 v75, 1.0, v75
	v_add_f32_e32 v68, 1.0, v68
	v_add_f32_e32 v69, 1.0, v69
	v_add_f32_e32 v70, 1.0, v70
	v_add_f32_e32 v71, 1.0, v71
	v_max_f32_e32 v74, 0, v74
	v_max_f32_e32 v75, 0, v75
	v_rcp_f32_e32 v68, v68
	v_rcp_f32_e32 v69, v69
	v_rcp_f32_e32 v70, v70
	s_nop 0
	v_mov_b32_e32 v158, v176
	v_mov_b32_e32 v159, v177
	v_lshlrev_b32_e32 v162, 16, v158
	v_and_b32_e32 v163, 0xffff0000, v158
	v_pk_mul_f32 v[126:127], v[122:123], v[162:163]
	v_add_f32_e32 v123, v128, v76
	v_mul_f32_e32 v123, 0xbfb8aa3b, v123
	v_exp_f32_e32 v123, v123
	v_add_f32_e32 v122, v124, v80
	v_mul_f32_e32 v122, 0xbfb8aa3b, v122
	v_exp_f32_e32 v122, v122
	v_add_f32_e32 v123, 1.0, v123
	v_rcp_f32_e32 v124, v123
	v_add_f32_e32 v123, v125, v81
	v_mul_f32_e32 v123, 0xbfb8aa3b, v123
	v_exp_f32_e32 v123, v123
	v_add_f32_e32 v122, 1.0, v122
	v_rcp_f32_e32 v122, v122
	v_add_f32_e32 v125, v129, v77
	v_add_f32_e32 v123, 1.0, v123
	v_rcp_f32_e32 v123, v123
	v_mul_f32_e32 v125, 0xbfb8aa3b, v125
	v_exp_f32_e32 v125, v125
	v_lshlrev_b32_e32 v158, 16, v159
	v_pk_mul_f32 v[128:129], v[122:123], v[132:133]
	v_and_b32_e32 v159, 0xffff0000, v159
	v_add_f32_e32 v122, v128, v128
	v_add_f32_e32 v123, v129, v129
	v_mul_f32_e32 v122, 0x3fb8aa3b, v122
	v_mul_f32_e32 v123, 0x3fb8aa3b, v123
	v_exp_f32_e32 v122, v122
	v_exp_f32_e32 v123, v123
	v_add_f32_e32 v125, 1.0, v125
	v_rcp_f32_e32 v125, v125
	v_sub_f32_e32 v122, 1.0, v122
	v_sub_f32_e32 v123, 1.0, v123
	v_max_f32_e32 v122, 0, v122
	v_max_f32_e32 v123, 0, v123
	v_sqrt_f32_e32 v122, v122
	v_sqrt_f32_e32 v123, v123
	v_cvt_pk_bf16_f32 v126, v126, v127
	v_rcp_f32_e32 v71, v71
	v_sqrt_f32_e32 v74, v74
	v_pk_mul_f32 v[122:123], v[124:125], v[122:123]
	v_sqrt_f32_e32 v75, v75
	v_pk_mul_f32 v[124:125], v[122:123], v[158:159]
	v_cvt_pk_bf16_f32 v159, v128, v129
	v_mad_i64_i32 v[128:129], s[6:7], v136, s84, v[130:131]
	v_lshl_add_u64 v[128:129], v[128:129], 0, v[146:147]
	v_add_co_u32_e32 v128, vcc, s69, v128
	v_add_u32_e32 v122, 16, v136
	v_cvt_pk_bf16_f32 v158, v160, v161
	v_addc_co_u32_e32 v129, vcc, 0, v129, vcc
	v_cvt_pk_bf16_f32 v127, v124, v125
	v_mov_b32_e32 v160, v158
	v_mov_b32_e32 v161, v159
	v_mov_b32_e32 v164, v126
	v_mov_b32_e32 v165, v127
	v_pk_mul_f32 v[126:127], v[114:115], v[134:135]
	v_ashrrev_i32_e32 v123, 31, v122
	v_lshlrev_b64 v[124:125], 11, v[122:123]
	v_lshl_add_u64 v[124:125], s[14:15], 0, v[124:125]
	v_lshl_add_u64 v[124:125], v[124:125], 0, v[146:147]
	s_nop 0
	v_add_f32_e32 v114, v126, v126
	v_add_f32_e32 v115, v127, v127
	v_mul_f32_e32 v114, 0x3fb8aa3b, v114
	v_mul_f32_e32 v115, 0x3fb8aa3b, v115
	v_exp_f32_e32 v114, v114
	v_exp_f32_e32 v115, v115
	v_pk_mul_f32 v[68:69], v[68:69], v[132:133]
	v_pk_mul_f32 v[70:71], v[70:71], v[74:75]
	v_sub_f32_e32 v114, 1.0, v114
	v_sub_f32_e32 v115, 1.0, v115
	v_max_f32_e32 v114, 0, v114
	v_max_f32_e32 v115, 0, v115
	v_sqrt_f32_e32 v114, v114
	v_sqrt_f32_e32 v115, v115
	v_add_f32_e32 v74, v68, v68
	v_add_f32_e32 v75, v69, v69
	v_add_f32_e32 v72, v72, v76
	v_pk_mul_f32 v[114:115], v[118:119], v[114:115]
	v_add_f32_e32 v73, v73, v77
	v_mul_f32_e32 v74, 0x3fb8aa3b, v74
	v_mul_f32_e32 v75, 0x3fb8aa3b, v75
	v_mul_f32_e32 v72, 0xbfb8aa3b, v72
	v_mul_f32_e32 v73, 0xbfb8aa3b, v73
	v_exp_f32_e32 v74, v74
	v_exp_f32_e32 v75, v75
	v_exp_f32_e32 v72, v72
	v_exp_f32_e32 v73, v73
	v_sub_f32_e32 v74, 1.0, v74
	v_sub_f32_e32 v75, 1.0, v75
	v_add_f32_e32 v72, 1.0, v72
	v_add_f32_e32 v73, 1.0, v73
	v_max_f32_e32 v74, 0, v74
	v_max_f32_e32 v75, 0, v75
	v_rcp_f32_e32 v72, v72
	v_rcp_f32_e32 v73, v73
	v_sqrt_f32_e32 v74, v74
	v_sqrt_f32_e32 v75, v75
	v_cvt_pk_bf16_f32 v66, v66, v67
	v_cvt_pk_bf16_f32 v67, v68, v69
	v_pk_mul_f32 v[72:73], v[72:73], v[74:75]
	v_or_b32_e32 v74, 4, v150
	v_ashrrev_i32_e32 v75, 31, v74
	s_nop 0
	v_mov_b32_e32 v124, v190
	v_mov_b32_e32 v125, v191
	v_lshlrev_b32_e32 v128, 16, v124
	v_and_b32_e32 v129, 0xffff0000, v124
	v_pk_mul_f32 v[118:119], v[114:115], v[128:129]
	v_add_f32_e32 v115, v120, v76
	v_mul_f32_e32 v115, 0xbfb8aa3b, v115
	v_exp_f32_e32 v115, v115
	v_add_f32_e32 v114, v116, v80
	v_mul_f32_e32 v114, 0xbfb8aa3b, v114
	v_exp_f32_e32 v114, v114
	v_add_f32_e32 v115, 1.0, v115
	v_rcp_f32_e32 v116, v115
	v_add_f32_e32 v115, v117, v81
	v_mul_f32_e32 v115, 0xbfb8aa3b, v115
	v_exp_f32_e32 v115, v115
	v_add_f32_e32 v114, 1.0, v114
	v_rcp_f32_e32 v114, v114
	v_add_f32_e32 v117, v121, v77
	v_add_f32_e32 v115, 1.0, v115
	v_rcp_f32_e32 v115, v115
	v_mul_f32_e32 v117, 0xbfb8aa3b, v117
	v_exp_f32_e32 v117, v117
	v_lshlrev_b32_e32 v124, 16, v125
	v_pk_mul_f32 v[120:121], v[114:115], v[132:133]
	v_and_b32_e32 v125, 0xffff0000, v125
	v_add_f32_e32 v114, v120, v120
	v_add_f32_e32 v115, v121, v121
	v_mul_f32_e32 v114, 0x3fb8aa3b, v114
	v_mul_f32_e32 v115, 0x3fb8aa3b, v115
	v_exp_f32_e32 v114, v114
	v_exp_f32_e32 v115, v115
	v_add_f32_e32 v117, 1.0, v117
	v_rcp_f32_e32 v117, v117
	v_sub_f32_e32 v114, 1.0, v114
	v_sub_f32_e32 v115, 1.0, v115
	v_max_f32_e32 v114, 0, v114
	v_max_f32_e32 v115, 0, v115
	v_sqrt_f32_e32 v114, v114
	v_sqrt_f32_e32 v115, v115
	v_cvt_pk_bf16_f32 v118, v118, v119
	v_pk_mul_f32 v[114:115], v[116:117], v[114:115]
	s_nop 0
	v_pk_mul_f32 v[116:117], v[114:115], v[124:125]
	v_cvt_pk_bf16_f32 v125, v120, v121
	v_mad_i64_i32 v[120:121], s[6:7], v122, s84, v[130:131]
	v_lshl_add_u64 v[120:121], v[120:121], 0, v[146:147]
	v_add_co_u32_e32 v120, vcc, s69, v120
	v_add_u32_e32 v114, 16, v122
	v_cvt_pk_bf16_f32 v124, v126, v127
	v_addc_co_u32_e32 v121, vcc, 0, v121, vcc
	v_cvt_pk_bf16_f32 v119, v116, v117
	v_mov_b32_e32 v188, v124
	v_mov_b32_e32 v189, v125
	v_mov_b32_e32 v228, v118
	v_mov_b32_e32 v229, v119
	v_pk_mul_f32 v[118:119], v[106:107], v[134:135]
	v_ashrrev_i32_e32 v115, 31, v114
	v_lshlrev_b64 v[116:117], 11, v[114:115]
	v_lshl_add_u64 v[116:117], s[14:15], 0, v[116:117]
	v_lshl_add_u64 v[116:117], v[116:117], 0, v[146:147]
	s_nop 0
	v_add_f32_e32 v106, v118, v118
	v_add_f32_e32 v107, v119, v119
	v_mul_f32_e32 v106, 0x3fb8aa3b, v106
	v_mul_f32_e32 v107, 0x3fb8aa3b, v107
	v_exp_f32_e32 v106, v106
	v_exp_f32_e32 v107, v107
	v_sub_f32_e32 v106, 1.0, v106
	v_sub_f32_e32 v107, 1.0, v107
	v_max_f32_e32 v106, 0, v106
	v_max_f32_e32 v107, 0, v107
	v_sqrt_f32_e32 v106, v106
	v_sqrt_f32_e32 v107, v107
	s_nop 0
	v_mov_b32_e32 v116, v192
	v_mov_b32_e32 v117, v193
	v_lshlrev_b32_e32 v120, 16, v116
	v_and_b32_e32 v121, 0xffff0000, v116
	v_pk_mul_f32 v[106:107], v[110:111], v[106:107]
	v_lshlrev_b32_e32 v116, 16, v117
	v_pk_mul_f32 v[110:111], v[106:107], v[120:121]
	v_add_f32_e32 v107, v112, v76
	v_mul_f32_e32 v107, 0xbfb8aa3b, v107
	v_exp_f32_e32 v107, v107
	v_add_f32_e32 v106, v108, v80
	v_mul_f32_e32 v106, 0xbfb8aa3b, v106
	v_exp_f32_e32 v106, v106
	v_add_f32_e32 v107, 1.0, v107
	v_rcp_f32_e32 v108, v107
	v_add_f32_e32 v107, v109, v81
	v_mul_f32_e32 v107, 0xbfb8aa3b, v107
	v_exp_f32_e32 v107, v107
	v_add_f32_e32 v106, 1.0, v106
	v_rcp_f32_e32 v106, v106
	v_add_f32_e32 v109, v113, v77
	v_add_f32_e32 v107, 1.0, v107
	v_rcp_f32_e32 v107, v107
	v_mul_f32_e32 v109, 0xbfb8aa3b, v109
	v_exp_f32_e32 v109, v109
	v_and_b32_e32 v117, 0xffff0000, v117
	v_pk_mul_f32 v[112:113], v[106:107], v[132:133]
	v_cvt_pk_bf16_f32 v110, v110, v111
	v_add_f32_e32 v106, v112, v112
	v_add_f32_e32 v107, v113, v113
	v_mul_f32_e32 v106, 0x3fb8aa3b, v106
	v_mul_f32_e32 v107, 0x3fb8aa3b, v107
	v_exp_f32_e32 v106, v106
	v_exp_f32_e32 v107, v107
	v_add_f32_e32 v109, 1.0, v109
	v_rcp_f32_e32 v109, v109
	v_sub_f32_e32 v106, 1.0, v106
	v_sub_f32_e32 v107, 1.0, v107
	v_max_f32_e32 v106, 0, v106
	v_max_f32_e32 v107, 0, v107
	v_sqrt_f32_e32 v106, v106
	v_sqrt_f32_e32 v107, v107
	s_nop 0
	v_pk_mul_f32 v[106:107], v[108:109], v[106:107]
	s_nop 0
	v_pk_mul_f32 v[108:109], v[106:107], v[116:117]
	v_cvt_pk_bf16_f32 v117, v112, v113
	v_mad_i64_i32 v[112:113], s[6:7], v114, s84, v[130:131]
	v_lshl_add_u64 v[112:113], v[112:113], 0, v[146:147]
	v_add_co_u32_e32 v112, vcc, s69, v112
	v_add_u32_e32 v106, 0x50, v114
	v_cvt_pk_bf16_f32 v116, v118, v119
	v_addc_co_u32_e32 v113, vcc, 0, v113, vcc
	v_cvt_pk_bf16_f32 v111, v108, v109
	v_mov_b32_e32 v120, v116
	v_mov_b32_e32 v121, v117
	v_mov_b32_e32 v124, v110
	v_mov_b32_e32 v125, v111
	v_pk_mul_f32 v[110:111], v[98:99], v[134:135]
	v_ashrrev_i32_e32 v107, 31, v106
	v_lshlrev_b64 v[108:109], 11, v[106:107]
	v_lshl_add_u64 v[108:109], s[14:15], 0, v[108:109]
	v_lshl_add_u64 v[108:109], v[108:109], 0, v[146:147]
	s_nop 0
	v_add_f32_e32 v98, v110, v110
	v_add_f32_e32 v99, v111, v111
	v_mul_f32_e32 v98, 0x3fb8aa3b, v98
	v_mul_f32_e32 v99, 0x3fb8aa3b, v99
	v_exp_f32_e32 v98, v98
	v_exp_f32_e32 v99, v99
	v_sub_f32_e32 v98, 1.0, v98
	v_sub_f32_e32 v99, 1.0, v99
	v_max_f32_e32 v98, 0, v98
	v_max_f32_e32 v99, 0, v99
	v_sqrt_f32_e32 v98, v98
	v_sqrt_f32_e32 v99, v99
	s_nop 0
	v_mov_b32_e32 v108, v194
	v_mov_b32_e32 v109, v195
	v_lshlrev_b32_e32 v112, 16, v108
	v_and_b32_e32 v113, 0xffff0000, v108
	v_pk_mul_f32 v[98:99], v[102:103], v[98:99]
	v_lshlrev_b32_e32 v108, 16, v109
	v_pk_mul_f32 v[102:103], v[98:99], v[112:113]
	v_add_f32_e32 v99, v104, v76
	v_mul_f32_e32 v99, 0xbfb8aa3b, v99
	v_exp_f32_e32 v99, v99
	v_add_f32_e32 v98, v100, v80
	v_mul_f32_e32 v98, 0xbfb8aa3b, v98
	v_exp_f32_e32 v98, v98
	v_add_f32_e32 v99, 1.0, v99
	v_rcp_f32_e32 v100, v99
	v_add_f32_e32 v99, v101, v81
	v_mul_f32_e32 v99, 0xbfb8aa3b, v99
	v_exp_f32_e32 v99, v99
	v_add_f32_e32 v98, 1.0, v98
	v_rcp_f32_e32 v98, v98
	v_add_f32_e32 v101, v105, v77
	v_add_f32_e32 v99, 1.0, v99
	v_rcp_f32_e32 v99, v99
	v_mul_f32_e32 v101, 0xbfb8aa3b, v101
	v_exp_f32_e32 v101, v101
	v_and_b32_e32 v109, 0xffff0000, v109
	v_pk_mul_f32 v[104:105], v[98:99], v[132:133]
	v_cvt_pk_bf16_f32 v102, v102, v103
	v_add_f32_e32 v98, v104, v104
	v_add_f32_e32 v99, v105, v105
	v_mul_f32_e32 v98, 0x3fb8aa3b, v98
	v_mul_f32_e32 v99, 0x3fb8aa3b, v99
	v_exp_f32_e32 v98, v98
	v_exp_f32_e32 v99, v99
	v_add_f32_e32 v101, 1.0, v101
	v_rcp_f32_e32 v101, v101
	v_sub_f32_e32 v98, 1.0, v98
	v_sub_f32_e32 v99, 1.0, v99
	v_max_f32_e32 v98, 0, v98
	v_max_f32_e32 v99, 0, v99
	v_sqrt_f32_e32 v98, v98
	v_sqrt_f32_e32 v99, v99
	s_nop 0
	v_pk_mul_f32 v[98:99], v[100:101], v[98:99]
	s_nop 0
	v_pk_mul_f32 v[100:101], v[98:99], v[108:109]
	v_cvt_pk_bf16_f32 v109, v104, v105
	v_mad_i64_i32 v[104:105], s[6:7], v106, s84, v[130:131]
	v_lshl_add_u64 v[104:105], v[104:105], 0, v[146:147]
	v_add_co_u32_e32 v104, vcc, s69, v104
	v_add_u32_e32 v98, 16, v106
	v_cvt_pk_bf16_f32 v108, v110, v111
	v_addc_co_u32_e32 v105, vcc, 0, v105, vcc
	v_cvt_pk_bf16_f32 v103, v100, v101
	v_mov_b32_e32 v112, v108
	v_mov_b32_e32 v113, v109
	v_mov_b32_e32 v116, v102
	v_mov_b32_e32 v117, v103
	v_pk_mul_f32 v[102:103], v[90:91], v[134:135]
	v_ashrrev_i32_e32 v99, 31, v98
	v_lshlrev_b64 v[100:101], 11, v[98:99]
	v_lshl_add_u64 v[100:101], s[14:15], 0, v[100:101]
	v_lshl_add_u64 v[100:101], v[100:101], 0, v[146:147]
	s_nop 0
	v_add_f32_e32 v90, v102, v102
	v_add_f32_e32 v91, v103, v103
	v_mul_f32_e32 v90, 0x3fb8aa3b, v90
	v_mul_f32_e32 v91, 0x3fb8aa3b, v91
	v_exp_f32_e32 v90, v90
	v_exp_f32_e32 v91, v91
	v_sub_f32_e32 v90, 1.0, v90
	v_sub_f32_e32 v91, 1.0, v91
	v_max_f32_e32 v90, 0, v90
	v_max_f32_e32 v91, 0, v91
	v_sqrt_f32_e32 v90, v90
	v_sqrt_f32_e32 v91, v91
	s_nop 0
	v_mov_b32_e32 v100, v196
	v_mov_b32_e32 v101, v197
	v_lshlrev_b32_e32 v104, 16, v100
	v_and_b32_e32 v105, 0xffff0000, v100
	v_pk_mul_f32 v[90:91], v[94:95], v[90:91]
	v_lshlrev_b32_e32 v100, 16, v101
	v_pk_mul_f32 v[94:95], v[90:91], v[104:105]
	v_add_f32_e32 v91, v96, v76
	v_mul_f32_e32 v91, 0xbfb8aa3b, v91
	v_exp_f32_e32 v91, v91
	v_add_f32_e32 v90, v92, v80
	v_mul_f32_e32 v90, 0xbfb8aa3b, v90
	v_exp_f32_e32 v90, v90
	v_add_f32_e32 v91, 1.0, v91
	v_rcp_f32_e32 v92, v91
	v_add_f32_e32 v91, v93, v81
	v_mul_f32_e32 v91, 0xbfb8aa3b, v91
	v_exp_f32_e32 v91, v91
	v_add_f32_e32 v90, 1.0, v90
	v_rcp_f32_e32 v90, v90
	v_add_f32_e32 v93, v97, v77
	v_add_f32_e32 v91, 1.0, v91
	v_rcp_f32_e32 v91, v91
	v_mul_f32_e32 v93, 0xbfb8aa3b, v93
	v_exp_f32_e32 v93, v93
	v_and_b32_e32 v101, 0xffff0000, v101
	v_pk_mul_f32 v[96:97], v[90:91], v[132:133]
	v_cvt_pk_bf16_f32 v94, v94, v95
	v_add_f32_e32 v90, v96, v96
	v_add_f32_e32 v91, v97, v97
	v_mul_f32_e32 v90, 0x3fb8aa3b, v90
	v_mul_f32_e32 v91, 0x3fb8aa3b, v91
	v_exp_f32_e32 v90, v90
	v_exp_f32_e32 v91, v91
	v_add_f32_e32 v93, 1.0, v93
	v_rcp_f32_e32 v93, v93
	v_sub_f32_e32 v90, 1.0, v90
	v_sub_f32_e32 v91, 1.0, v91
	v_max_f32_e32 v90, 0, v90
	v_max_f32_e32 v91, 0, v91
	v_sqrt_f32_e32 v90, v90
	v_sqrt_f32_e32 v91, v91
	s_nop 0
	v_pk_mul_f32 v[90:91], v[92:93], v[90:91]
	s_nop 0
	v_pk_mul_f32 v[92:93], v[90:91], v[100:101]
	v_cvt_pk_bf16_f32 v101, v96, v97
	v_mad_i64_i32 v[96:97], s[6:7], v98, s84, v[130:131]
	v_lshl_add_u64 v[96:97], v[96:97], 0, v[146:147]
	v_add_co_u32_e32 v96, vcc, s69, v96
	v_add_u32_e32 v90, 16, v98
	v_cvt_pk_bf16_f32 v100, v102, v103
	v_addc_co_u32_e32 v97, vcc, 0, v97, vcc
	v_cvt_pk_bf16_f32 v95, v92, v93
	v_mov_b32_e32 v104, v100
	v_mov_b32_e32 v105, v101
	v_mov_b32_e32 v108, v94
	v_mov_b32_e32 v109, v95
	v_pk_mul_f32 v[94:95], v[82:83], v[134:135]
	v_ashrrev_i32_e32 v91, 31, v90
	v_lshlrev_b64 v[92:93], 11, v[90:91]
	v_lshl_add_u64 v[92:93], s[14:15], 0, v[92:93]
	v_lshl_add_u64 v[92:93], v[92:93], 0, v[146:147]
	s_nop 0
	v_add_f32_e32 v82, v94, v94
	v_add_f32_e32 v83, v95, v95
	v_mul_f32_e32 v82, 0x3fb8aa3b, v82
	v_mul_f32_e32 v83, 0x3fb8aa3b, v83
	v_exp_f32_e32 v82, v82
	v_exp_f32_e32 v83, v83
	v_sub_f32_e32 v82, 1.0, v82
	v_sub_f32_e32 v83, 1.0, v83
	v_max_f32_e32 v82, 0, v82
	v_max_f32_e32 v83, 0, v83
	v_sqrt_f32_e32 v82, v82
	v_sqrt_f32_e32 v83, v83
	s_nop 0
	v_mov_b32_e32 v92, v198
	v_mov_b32_e32 v93, v199
	v_lshlrev_b32_e32 v96, 16, v92
	v_and_b32_e32 v97, 0xffff0000, v92
	v_pk_mul_f32 v[82:83], v[86:87], v[82:83]
	v_lshlrev_b32_e32 v92, 16, v93
	v_pk_mul_f32 v[86:87], v[82:83], v[96:97]
	v_add_f32_e32 v83, v88, v76
	v_mul_f32_e32 v83, 0xbfb8aa3b, v83
	v_exp_f32_e32 v83, v83
	v_add_f32_e32 v82, v84, v80
	v_mul_f32_e32 v82, 0xbfb8aa3b, v82
	v_exp_f32_e32 v82, v82
	v_add_f32_e32 v83, 1.0, v83
	v_rcp_f32_e32 v84, v83
	v_add_f32_e32 v83, v85, v81
	v_mul_f32_e32 v83, 0xbfb8aa3b, v83
	v_exp_f32_e32 v83, v83
	v_add_f32_e32 v82, 1.0, v82
	v_rcp_f32_e32 v82, v82
	v_add_f32_e32 v85, v89, v77
	v_add_f32_e32 v83, 1.0, v83
	v_rcp_f32_e32 v83, v83
	v_mul_f32_e32 v85, 0xbfb8aa3b, v85
	v_exp_f32_e32 v85, v85
	v_and_b32_e32 v93, 0xffff0000, v93
	v_pk_mul_f32 v[88:89], v[82:83], v[132:133]
	v_cvt_pk_bf16_f32 v86, v86, v87
	v_add_f32_e32 v82, v88, v88
	v_add_f32_e32 v83, v89, v89
	v_mul_f32_e32 v82, 0x3fb8aa3b, v82
	v_mul_f32_e32 v83, 0x3fb8aa3b, v83
	v_exp_f32_e32 v82, v82
	v_exp_f32_e32 v83, v83
	v_add_f32_e32 v85, 1.0, v85
	v_rcp_f32_e32 v85, v85
	v_sub_f32_e32 v82, 1.0, v82
	v_sub_f32_e32 v83, 1.0, v83
	v_max_f32_e32 v82, 0, v82
	v_max_f32_e32 v83, 0, v83
	v_sqrt_f32_e32 v82, v82
	v_sqrt_f32_e32 v83, v83
	s_nop 0
	v_pk_mul_f32 v[82:83], v[84:85], v[82:83]
	s_nop 0
	v_pk_mul_f32 v[84:85], v[82:83], v[92:93]
	v_cvt_pk_bf16_f32 v93, v88, v89
	v_mad_i64_i32 v[88:89], s[6:7], v90, s84, v[130:131]
	v_lshl_add_u64 v[88:89], v[88:89], 0, v[146:147]
	v_add_co_u32_e32 v88, vcc, s69, v88
	v_add_u32_e32 v82, 16, v90
	v_cvt_pk_bf16_f32 v92, v94, v95
	v_addc_co_u32_e32 v89, vcc, 0, v89, vcc
	v_cvt_pk_bf16_f32 v87, v84, v85
	v_mov_b32_e32 v96, v92
	v_mov_b32_e32 v97, v93
	v_mov_b32_e32 v100, v86
	v_mov_b32_e32 v101, v87
	s_nop 0
	v_ashrrev_i32_e32 v83, 31, v82
	v_lshlrev_b64 v[84:85], 11, v[82:83]
	v_lshl_add_u64 v[84:85], s[14:15], 0, v[84:85]
	v_lshl_add_u64 v[84:85], v[84:85], 0, v[146:147]
	s_nop 0
	v_mad_i64_i32 v[68:69], s[6:7], v82, s84, v[130:131]
	v_lshl_add_u64 v[68:69], v[68:69], 0, v[146:147]
	v_add_co_u32_e32 v68, vcc, s69, v68
	s_nop 0
	v_mov_b32_e32 v84, v200
	v_mov_b32_e32 v85, v201
	v_lshlrev_b32_e32 v78, 16, v84
	v_and_b32_e32 v79, 0xffff0000, v84
	v_lshlrev_b32_e32 v76, 16, v85
	v_and_b32_e32 v77, 0xffff0000, v85
	v_pk_mul_f32 v[70:71], v[70:71], v[78:79]
	v_pk_mul_f32 v[72:73], v[72:73], v[76:77]
	v_addc_co_u32_e32 v69, vcc, 0, v69, vcc
	v_mov_b32_e32 v88, v66
	v_mov_b32_e32 v89, v67
	v_cvt_pk_bf16_f32 v66, v70, v71
	v_cvt_pk_bf16_f32 v67, v72, v73
	v_mov_b32_e32 v92, v66
	v_mov_b32_e32 v93, v67
	v_mov_b32_e32 v70, v236
	v_mov_b32_e32 v71, v237
	v_mov_b32_e32 v72, v238
	v_mov_b32_e32 v73, v239
	s_nop 0
	v_mov_b32_e32 v66, v246
	v_mov_b32_e32 v67, v247
	v_mov_b32_e32 v68, v248
	v_mov_b32_e32 v69, v249
	v_mov_b32_e32 v76, v250
	v_mov_b32_e32 v77, v251
	v_mov_b32_e32 v78, v252
	v_mov_b32_e32 v79, v253
	s_waitcnt vmcnt(0)
	v_add_f32_e32 v58, v58, v70
	v_ashrrev_i32_e32 v149, 31, v148
	v_max_f32_e64 v80, -v76, -v76
	v_mul_f32_e64 v76, |v76|, s72
	v_exp_f32_e32 v76, v76
	v_mul_f32_e32 v58, 0xbfb8aa3b, v58
	v_exp_f32_e32 v58, v58
	v_max_f32_e32 v80, 0, v80
	v_add_f32_e32 v76, 1.0, v76
	v_cmp_gt_f32_e32 vcc, s71, v76
	v_add_f32_e32 v58, 1.0, v58
	v_rcp_f32_e32 v86, v58
	v_cndmask_b32_e64 v81, 0, 32, vcc
	v_ldexp_f32 v76, v76, v81
	v_log_f32_e32 v76, v76
	v_add_f32_e32 v58, v62, v66
	v_mul_f32_e32 v58, 0xbfb8aa3b, v58
	v_exp_f32_e32 v58, v58
	v_mul_f32_e32 v81, 0x3f317217, v76
	v_fma_f32 v81, v76, s73, -v81
	v_fmac_f32_e32 v81, 0x3377d1cf, v76
	v_fmac_f32_e32 v81, 0x3f317217, v76
	v_cmp_lt_f32_e64 s[6:7], |v76|, s74
	v_add_f32_e32 v58, 1.0, v58
	v_rcp_f32_e32 v62, v58
	v_cndmask_b32_e64 v76, v76, v81, s[6:7]
	v_cndmask_b32_e32 v81, 0, v243, vcc
	v_sub_f32_e32 v82, v76, v81
	v_max_f32_e64 v76, -v77, -v77
	v_max_f32_e32 v81, 0, v76
	v_mul_f32_e64 v76, |v77|, s72
	v_exp_f32_e32 v76, v76
	v_add_f32_e32 v58, v59, v71
	v_mul_f32_e32 v58, 0xbfb8aa3b, v58
	v_exp_f32_e32 v58, v58
	v_add_f32_e32 v76, 1.0, v76
	v_cmp_gt_f32_e32 vcc, s71, v76
	v_add_f32_e32 v60, v60, v72
	v_add_f32_e32 v58, 1.0, v58
	v_cndmask_b32_e64 v77, 0, 32, vcc
	v_ldexp_f32 v76, v76, v77
	v_log_f32_e32 v76, v76
	v_rcp_f32_e32 v87, v58
	v_add_f32_e32 v58, v63, v67
	v_mul_f32_e32 v58, 0xbfb8aa3b, v58
	v_mul_f32_e32 v77, 0x3f317217, v76
	v_fma_f32 v77, v76, s73, -v77
	v_fmac_f32_e32 v77, 0x3377d1cf, v76
	v_fmac_f32_e32 v77, 0x3f317217, v76
	v_cmp_lt_f32_e64 s[6:7], |v76|, s74
	v_exp_f32_e32 v58, v58
	v_mul_f32_e32 v60, 0xbfb8aa3b, v60
	v_cndmask_b32_e64 v76, v76, v77, s[6:7]
	v_cndmask_b32_e32 v77, 0, v243, vcc
	v_sub_f32_e32 v83, v76, v77
	v_mul_f32_e64 v77, |v78|, s72
	v_exp_f32_e32 v77, v77
	v_max_f32_e64 v76, -v78, -v78
	v_add_f32_e32 v58, 1.0, v58
	v_rcp_f32_e32 v63, v58
	v_add_f32_e32 v77, 1.0, v77
	v_cmp_gt_f32_e32 vcc, s71, v77
	v_pk_add_f32 v[58:59], v[80:81], v[82:83]
	v_exp_f32_e32 v60, v60
	v_cndmask_b32_e64 v78, 0, 32, vcc
	v_ldexp_f32 v77, v77, v78
	v_log_f32_e32 v77, v77
	v_pk_mul_f32 v[58:59], v[58:59], s[2:3] op_sel_hi:[1,0]
	v_add_f32_e32 v60, 1.0, v60
	v_pk_mul_f32 v[80:81], v[86:87], v[58:59]
	v_mul_f32_e32 v78, 0x3f317217, v77
	v_fma_f32 v78, v77, s73, -v78
	v_fmac_f32_e32 v78, 0x3377d1cf, v77
	v_fmac_f32_e32 v78, 0x3f317217, v77
	v_cmp_lt_f32_e64 s[6:7], |v77|, s74
	v_add_f32_e32 v82, v80, v80
	v_add_f32_e32 v83, v81, v81
	v_cndmask_b32_e64 v77, v77, v78, s[6:7]
	v_cndmask_b32_e32 v78, 0, v243, vcc
	v_sub_f32_e32 v78, v77, v78
	v_max_f32_e64 v77, -v79, -v79
	v_mul_f32_e64 v79, |v79|, s72
	v_exp_f32_e32 v79, v79
	v_mul_f32_e32 v82, 0x3fb8aa3b, v82
	v_mul_f32_e32 v83, 0x3fb8aa3b, v83
	v_exp_f32_e32 v82, v82
	v_add_f32_e32 v79, 1.0, v79
	v_cmp_gt_f32_e32 vcc, s71, v79
	v_exp_f32_e32 v83, v83
	v_sub_f32_e32 v82, 1.0, v82
	v_cndmask_b32_e64 v84, 0, 32, vcc
	v_ldexp_f32 v79, v79, v84
	v_log_f32_e32 v79, v79
	v_sub_f32_e32 v83, 1.0, v83
	v_max_f32_e32 v82, 0, v82
	v_max_f32_e32 v83, 0, v83
	v_mul_f32_e32 v84, 0x3f317217, v79
	v_fma_f32 v84, v79, s73, -v84
	v_fmac_f32_e32 v84, 0x3377d1cf, v79
	v_fmac_f32_e32 v84, 0x3f317217, v79
	v_cmp_lt_f32_e64 s[6:7], |v79|, s74
	v_sqrt_f32_e32 v82, v82
	v_sqrt_f32_e32 v83, v83
	v_cndmask_b32_e64 v79, v79, v84, s[6:7]
	v_cndmask_b32_e32 v84, 0, v243, vcc
	v_sub_f32_e32 v79, v79, v84
	v_lshlrev_b64 v[84:85], 11, v[148:149]
	v_lshl_add_u64 v[84:85], s[14:15], 0, v[84:85]
	v_lshl_add_u64 v[84:85], v[84:85], 0, v[146:147]
	s_nop 0
	v_pk_mul_f32 v[62:63], v[62:63], v[82:83]
	v_max_f32_e32 v76, 0, v76
	v_max_f32_e32 v77, 0, v77
	v_add_f32_e32 v50, v50, v70
	v_add_f32_e32 v51, v51, v71
	v_mul_f32_e32 v50, 0xbfb8aa3b, v50
	v_mul_f32_e32 v51, 0xbfb8aa3b, v51
	v_exp_f32_e32 v50, v50
	v_exp_f32_e32 v51, v51
	v_add_f32_e32 v54, v54, v66
	v_add_f32_e32 v55, v55, v67
	v_add_f32_e32 v50, 1.0, v50
	v_add_f32_e32 v51, 1.0, v51
	v_rcp_f32_e32 v50, v50
	v_rcp_f32_e32 v51, v51
	v_mul_f32_e32 v54, 0xbfb8aa3b, v54
	v_mul_f32_e32 v55, 0xbfb8aa3b, v55
	v_exp_f32_e32 v54, v54
	v_exp_f32_e32 v55, v55
	v_add_f32_e32 v42, v42, v70
	v_add_f32_e32 v43, v43, v71
	v_add_f32_e32 v54, 1.0, v54
	v_add_f32_e32 v55, 1.0, v55
	v_rcp_f32_e32 v54, v54
	v_rcp_f32_e32 v55, v55
	v_mul_f32_e32 v42, 0xbfb8aa3b, v42
	v_mul_f32_e32 v43, 0xbfb8aa3b, v43
	v_exp_f32_e32 v42, v42
	v_exp_f32_e32 v43, v43
	v_add_f32_e32 v46, v46, v66
	v_add_f32_e32 v47, v47, v67
	v_add_f32_e32 v42, 1.0, v42
	v_add_f32_e32 v43, 1.0, v43
	v_rcp_f32_e32 v42, v42
	v_rcp_f32_e32 v43, v43
	v_mul_f32_e32 v46, 0xbfb8aa3b, v46
	v_mul_f32_e32 v47, 0xbfb8aa3b, v47
	v_exp_f32_e32 v46, v46
	v_exp_f32_e32 v47, v47
	v_add_f32_e32 v34, v34, v70
	v_add_f32_e32 v35, v35, v71
	v_add_f32_e32 v46, 1.0, v46
	v_add_f32_e32 v47, 1.0, v47
	v_rcp_f32_e32 v46, v46
	v_rcp_f32_e32 v47, v47
	v_mul_f32_e32 v34, 0xbfb8aa3b, v34
	v_mul_f32_e32 v35, 0xbfb8aa3b, v35
	v_exp_f32_e32 v34, v34
	v_exp_f32_e32 v35, v35
	v_add_f32_e32 v38, v38, v66
	v_add_f32_e32 v39, v39, v67
	v_add_f32_e32 v34, 1.0, v34
	v_add_f32_e32 v35, 1.0, v35
	v_rcp_f32_e32 v34, v34
	v_rcp_f32_e32 v35, v35
	v_mul_f32_e32 v38, 0xbfb8aa3b, v38
	v_mul_f32_e32 v39, 0xbfb8aa3b, v39
	v_exp_f32_e32 v38, v38
	v_exp_f32_e32 v39, v39
	v_add_f32_e32 v26, v26, v70
	v_add_f32_e32 v27, v27, v71
	v_add_f32_e32 v38, 1.0, v38
	v_add_f32_e32 v39, 1.0, v39
	v_rcp_f32_e32 v38, v38
	v_rcp_f32_e32 v39, v39
	v_mul_f32_e32 v26, 0xbfb8aa3b, v26
	v_mul_f32_e32 v27, 0xbfb8aa3b, v27
	v_exp_f32_e32 v26, v26
	v_exp_f32_e32 v27, v27
	v_add_f32_e32 v30, v30, v66
	v_add_f32_e32 v31, v31, v67
	v_add_f32_e32 v26, 1.0, v26
	v_add_f32_e32 v27, 1.0, v27
	v_rcp_f32_e32 v26, v26
	v_rcp_f32_e32 v27, v27
	v_mul_f32_e32 v30, 0xbfb8aa3b, v30
	v_mul_f32_e32 v31, 0xbfb8aa3b, v31
	v_exp_f32_e32 v30, v30
	v_exp_f32_e32 v31, v31
	s_nop 0
	v_mov_b32_e32 v84, v202
	v_mov_b32_e32 v85, v203
	v_lshlrev_b32_e32 v86, 16, v84
	v_and_b32_e32 v87, 0xffff0000, v84
	v_pk_mul_f32 v[82:83], v[62:63], v[86:87]
	v_rcp_f32_e32 v62, v60
	v_add_f32_e32 v60, v64, v68
	v_mul_f32_e32 v60, 0xbfb8aa3b, v60
	v_exp_f32_e32 v60, v60
	v_add_f32_e32 v30, 1.0, v30
	v_add_f32_e32 v31, 1.0, v31
	v_rcp_f32_e32 v30, v30
	v_add_f32_e32 v60, 1.0, v60
	v_rcp_f32_e32 v64, v60
	v_add_f32_e32 v60, v61, v73
	v_mul_f32_e32 v60, 0xbfb8aa3b, v60
	v_exp_f32_e32 v60, v60
	v_rcp_f32_e32 v31, v31
	v_add_f32_e32 v18, v18, v70
	v_add_f32_e32 v19, v19, v71
	v_add_f32_e32 v60, 1.0, v60
	v_rcp_f32_e32 v63, v60
	v_add_f32_e32 v60, v65, v69
	v_mul_f32_e32 v60, 0xbfb8aa3b, v60
	v_exp_f32_e32 v60, v60
	v_mul_f32_e32 v18, 0xbfb8aa3b, v18
	v_mul_f32_e32 v19, 0xbfb8aa3b, v19
	v_exp_f32_e32 v18, v18
	v_add_f32_e32 v60, 1.0, v60
	v_rcp_f32_e32 v65, v60
	v_pk_add_f32 v[60:61], v[76:77], v[78:79]
	v_lshlrev_b32_e32 v78, 16, v85
	v_pk_mul_f32 v[60:61], v[60:61], s[2:3] op_sel_hi:[1,0]
	v_and_b32_e32 v79, 0xffff0000, v85
	v_pk_mul_f32 v[62:63], v[62:63], v[60:61]
	v_exp_f32_e32 v19, v19
	v_add_f32_e32 v76, v62, v62
	v_add_f32_e32 v77, v63, v63
	v_mul_f32_e32 v76, 0x3fb8aa3b, v76
	v_mul_f32_e32 v77, 0x3fb8aa3b, v77
	v_exp_f32_e32 v76, v76
	v_exp_f32_e32 v77, v77
	v_add_f32_e32 v18, 1.0, v18
	v_add_f32_e32 v19, 1.0, v19
	v_sub_f32_e32 v76, 1.0, v76
	v_sub_f32_e32 v77, 1.0, v77
	v_max_f32_e32 v76, 0, v76
	v_max_f32_e32 v77, 0, v77
	v_sqrt_f32_e32 v76, v76
	v_sqrt_f32_e32 v77, v77
	v_rcp_f32_e32 v18, v18
	v_rcp_f32_e32 v19, v19
	v_add_f32_e32 v22, v22, v66
	v_pk_mul_f32 v[64:65], v[64:65], v[76:77]
	v_add_f32_e32 v23, v23, v67
	v_pk_mul_f32 v[76:77], v[64:65], v[78:79]
	v_cvt_pk_bf16_f32 v78, v80, v81
	v_cvt_pk_bf16_f32 v79, v62, v63
	v_mad_i64_i32 v[80:81], s[6:7], v148, s84, v[130:131]
	v_lshlrev_b64 v[62:63], 1, v[74:75]
	v_lshl_add_u64 v[74:75], v[80:81], 0, v[62:63]
	v_add_co_u32_e32 v74, vcc, s69, v74
	v_add_u32_e32 v64, 16, v148
	s_nop 0
	v_addc_co_u32_e32 v75, vcc, 0, v75, vcc
	v_mov_b32_e32 v222, v78
	v_mov_b32_e32 v223, v79
	global_store_dwordx4 v[74:75], v[220:223], off offset:2040
	v_cvt_pk_bf16_f32 v78, v82, v83
	v_cvt_pk_bf16_f32 v79, v76, v77
	v_mov_b32_e32 v226, v78
	v_mov_b32_e32 v227, v79
	global_store_dwordx4 v[74:75], v[224:227], off offset:-8
	v_pk_mul_f32 v[76:77], v[50:51], v[58:59]
	v_ashrrev_i32_e32 v65, 31, v64
	v_lshlrev_b64 v[74:75], 11, v[64:65]
	v_lshl_add_u64 v[74:75], s[14:15], 0, v[74:75]
	v_lshl_add_u64 v[74:75], v[74:75], 0, v[146:147]
	s_nop 0
	v_add_f32_e32 v50, v76, v76
	v_add_f32_e32 v51, v77, v77
	v_mul_f32_e32 v50, 0x3fb8aa3b, v50
	v_mul_f32_e32 v51, 0x3fb8aa3b, v51
	v_exp_f32_e32 v50, v50
	v_exp_f32_e32 v51, v51
	v_mul_f32_e32 v22, 0xbfb8aa3b, v22
	v_mul_f32_e32 v23, 0xbfb8aa3b, v23
	v_sub_f32_e32 v50, 1.0, v50
	v_sub_f32_e32 v51, 1.0, v51
	v_max_f32_e32 v50, 0, v50
	v_max_f32_e32 v51, 0, v51
	v_sqrt_f32_e32 v50, v50
	v_sqrt_f32_e32 v51, v51
	v_exp_f32_e32 v22, v22
	v_exp_f32_e32 v23, v23
	v_add_f32_e32 v10, v10, v70
	v_pk_mul_f32 v[50:51], v[54:55], v[50:51]
	v_add_f32_e32 v22, 1.0, v22
	v_add_f32_e32 v23, 1.0, v23
	v_rcp_f32_e32 v22, v22
	v_rcp_f32_e32 v23, v23
	v_add_f32_e32 v11, v11, v71
	v_mul_f32_e32 v10, 0xbfb8aa3b, v10
	v_mul_f32_e32 v11, 0xbfb8aa3b, v11
	v_exp_f32_e32 v10, v10
	v_exp_f32_e32 v11, v11
	v_add_f32_e32 v14, v14, v66
	v_add_f32_e32 v15, v15, v67
	v_add_f32_e32 v10, 1.0, v10
	v_add_f32_e32 v11, 1.0, v11
	v_rcp_f32_e32 v10, v10
	v_rcp_f32_e32 v11, v11
	v_mul_f32_e32 v14, 0xbfb8aa3b, v14
	v_mul_f32_e32 v15, 0xbfb8aa3b, v15
	v_exp_f32_e32 v14, v14
	v_exp_f32_e32 v15, v15
	v_add_f32_e32 v2, v2, v70
	v_add_f32_e32 v3, v3, v71
	v_add_f32_e32 v14, 1.0, v14
	v_add_f32_e32 v15, 1.0, v15
	v_rcp_f32_e32 v14, v14
	v_rcp_f32_e32 v15, v15
	v_mul_f32_e32 v2, 0xbfb8aa3b, v2
	v_mul_f32_e32 v3, 0xbfb8aa3b, v3
	v_exp_f32_e32 v2, v2
	v_exp_f32_e32 v3, v3
	v_add_f32_e32 v4, v4, v72
	v_add_f32_e32 v5, v5, v73
	v_add_f32_e32 v2, 1.0, v2
	v_add_f32_e32 v3, 1.0, v3
	v_rcp_f32_e32 v2, v2
	v_rcp_f32_e32 v3, v3
	v_mul_f32_e32 v4, 0xbfb8aa3b, v4
	v_mul_f32_e32 v5, 0xbfb8aa3b, v5
	v_exp_f32_e32 v4, v4
	v_pk_mul_f32 v[2:3], v[2:3], v[58:59]
	v_exp_f32_e32 v5, v5
	v_add_f32_e32 v6, v6, v66
	v_add_f32_e32 v4, 1.0, v4
	v_rcp_f32_e32 v4, v4
	v_add_f32_e32 v5, 1.0, v5
	v_rcp_f32_e32 v5, v5
	v_add_f32_e32 v7, v7, v67
	v_mul_f32_e32 v6, 0xbfb8aa3b, v6
	v_mul_f32_e32 v7, 0xbfb8aa3b, v7
	v_exp_f32_e32 v6, v6
	v_exp_f32_e32 v7, v7
	v_pk_mul_f32 v[4:5], v[4:5], v[60:61]
	v_add_f32_e32 v8, v8, v68
	v_add_f32_e32 v6, 1.0, v6
	v_add_f32_e32 v7, 1.0, v7
	v_rcp_f32_e32 v6, v6
	v_rcp_f32_e32 v7, v7
	v_add_f32_e32 v9, v9, v69
	v_mul_f32_e32 v8, 0xbfb8aa3b, v8
	v_mul_f32_e32 v9, 0xbfb8aa3b, v9
	v_exp_f32_e32 v8, v8
	v_exp_f32_e32 v9, v9
	s_nop 0
	v_mov_b32_e32 v74, v204
	v_mov_b32_e32 v75, v205
	v_lshlrev_b32_e32 v78, 16, v74
	v_and_b32_e32 v79, 0xffff0000, v74
	v_pk_mul_f32 v[54:55], v[50:51], v[78:79]
	v_add_f32_e32 v51, v56, v68
	v_mul_f32_e32 v51, 0xbfb8aa3b, v51
	v_exp_f32_e32 v51, v51
	v_add_f32_e32 v50, v52, v72
	v_mul_f32_e32 v50, 0xbfb8aa3b, v50
	v_exp_f32_e32 v50, v50
	v_add_f32_e32 v51, 1.0, v51
	v_rcp_f32_e32 v52, v51
	v_add_f32_e32 v51, v53, v73
	v_mul_f32_e32 v51, 0xbfb8aa3b, v51
	v_exp_f32_e32 v51, v51
	v_add_f32_e32 v50, 1.0, v50
	v_rcp_f32_e32 v50, v50
	v_add_f32_e32 v53, v57, v69
	v_add_f32_e32 v51, 1.0, v51
	v_rcp_f32_e32 v51, v51
	v_mul_f32_e32 v53, 0xbfb8aa3b, v53
	v_exp_f32_e32 v53, v53
	v_lshlrev_b32_e32 v74, 16, v75
	v_pk_mul_f32 v[56:57], v[50:51], v[60:61]
	v_and_b32_e32 v75, 0xffff0000, v75
	v_add_f32_e32 v50, v56, v56
	v_add_f32_e32 v51, v57, v57
	v_mul_f32_e32 v50, 0x3fb8aa3b, v50
	v_mul_f32_e32 v51, 0x3fb8aa3b, v51
	v_exp_f32_e32 v50, v50
	v_exp_f32_e32 v51, v51
	v_add_f32_e32 v53, 1.0, v53
	v_rcp_f32_e32 v53, v53
	v_sub_f32_e32 v50, 1.0, v50
	v_sub_f32_e32 v51, 1.0, v51
	v_max_f32_e32 v50, 0, v50
	v_max_f32_e32 v51, 0, v51
	v_sqrt_f32_e32 v50, v50
	v_sqrt_f32_e32 v51, v51
	v_cvt_pk_bf16_f32 v54, v54, v55
	v_add_f32_e32 v8, 1.0, v8
	v_add_f32_e32 v9, 1.0, v9
	v_pk_mul_f32 v[50:51], v[52:53], v[50:51]
	v_rcp_f32_e32 v8, v8
	v_pk_mul_f32 v[52:53], v[50:51], v[74:75]
	v_cvt_pk_bf16_f32 v75, v56, v57
	v_mad_i64_i32 v[56:57], s[6:7], v64, s84, v[130:131]
	v_lshl_add_u64 v[56:57], v[56:57], 0, v[62:63]
	v_add_co_u32_e32 v56, vcc, s69, v56
	v_add_u32_e32 v50, 16, v64
	v_cvt_pk_bf16_f32 v74, v76, v77
	v_addc_co_u32_e32 v57, vcc, 0, v57, vcc
	v_cvt_pk_bf16_f32 v55, v52, v53
	v_mov_b32_e32 v162, v74
	v_mov_b32_e32 v163, v75
	global_store_dwordx4 v[56:57], v[160:163], off offset:2040
	v_mov_b32_e32 v166, v54
	v_mov_b32_e32 v167, v55
	global_store_dwordx4 v[56:57], v[164:167], off offset:-8
	v_pk_mul_f32 v[54:55], v[42:43], v[58:59]
	v_ashrrev_i32_e32 v51, 31, v50
	v_lshlrev_b64 v[52:53], 11, v[50:51]
	v_lshl_add_u64 v[52:53], s[14:15], 0, v[52:53]
	v_lshl_add_u64 v[52:53], v[52:53], 0, v[146:147]
	s_nop 0
	v_add_f32_e32 v42, v54, v54
	v_add_f32_e32 v43, v55, v55
	v_mul_f32_e32 v42, 0x3fb8aa3b, v42
	v_mul_f32_e32 v43, 0x3fb8aa3b, v43
	v_exp_f32_e32 v42, v42
	v_exp_f32_e32 v43, v43
	v_rcp_f32_e32 v9, v9
	s_mov_b32 s2, s22
	v_sub_f32_e32 v42, 1.0, v42
	v_sub_f32_e32 v43, 1.0, v43
	v_max_f32_e32 v42, 0, v42
	v_max_f32_e32 v43, 0, v43
	v_sqrt_f32_e32 v42, v42
	v_sqrt_f32_e32 v43, v43
	s_nop 0
	v_mov_b32_e32 v52, v206
	v_mov_b32_e32 v53, v207
	v_lshlrev_b32_e32 v56, 16, v52
	v_and_b32_e32 v57, 0xffff0000, v52
	v_pk_mul_f32 v[42:43], v[46:47], v[42:43]
	v_lshlrev_b32_e32 v52, 16, v53
	v_pk_mul_f32 v[46:47], v[42:43], v[56:57]
	v_add_f32_e32 v43, v48, v68
	v_mul_f32_e32 v43, 0xbfb8aa3b, v43
	v_exp_f32_e32 v43, v43
	v_add_f32_e32 v42, v44, v72
	v_mul_f32_e32 v42, 0xbfb8aa3b, v42
	v_exp_f32_e32 v42, v42
	v_add_f32_e32 v43, 1.0, v43
	v_rcp_f32_e32 v44, v43
	v_add_f32_e32 v43, v45, v73
	v_mul_f32_e32 v43, 0xbfb8aa3b, v43
	v_exp_f32_e32 v43, v43
	v_add_f32_e32 v42, 1.0, v42
	v_rcp_f32_e32 v42, v42
	v_add_f32_e32 v45, v49, v69
	v_add_f32_e32 v43, 1.0, v43
	v_rcp_f32_e32 v43, v43
	v_mul_f32_e32 v45, 0xbfb8aa3b, v45
	v_exp_f32_e32 v45, v45
	v_and_b32_e32 v53, 0xffff0000, v53
	v_pk_mul_f32 v[48:49], v[42:43], v[60:61]
	v_cvt_pk_bf16_f32 v46, v46, v47
	v_add_f32_e32 v42, v48, v48
	v_add_f32_e32 v43, v49, v49
	v_mul_f32_e32 v42, 0x3fb8aa3b, v42
	v_mul_f32_e32 v43, 0x3fb8aa3b, v43
	v_exp_f32_e32 v42, v42
	v_exp_f32_e32 v43, v43
	v_add_f32_e32 v45, 1.0, v45
	v_rcp_f32_e32 v45, v45
	v_sub_f32_e32 v42, 1.0, v42
	v_sub_f32_e32 v43, 1.0, v43
	v_max_f32_e32 v42, 0, v42
	v_max_f32_e32 v43, 0, v43
	v_sqrt_f32_e32 v42, v42
	v_sqrt_f32_e32 v43, v43
	s_nop 0
	v_pk_mul_f32 v[42:43], v[44:45], v[42:43]
	s_nop 0
	v_pk_mul_f32 v[44:45], v[42:43], v[52:53]
	v_cvt_pk_bf16_f32 v53, v48, v49
	v_mad_i64_i32 v[48:49], s[6:7], v50, s84, v[130:131]
	v_lshl_add_u64 v[48:49], v[48:49], 0, v[62:63]
	v_add_co_u32_e32 v48, vcc, s69, v48
	v_add_u32_e32 v42, 16, v50
	v_cvt_pk_bf16_f32 v52, v54, v55
	v_addc_co_u32_e32 v49, vcc, 0, v49, vcc
	v_cvt_pk_bf16_f32 v47, v44, v45
	v_mov_b32_e32 v190, v52
	v_mov_b32_e32 v191, v53
	global_store_dwordx4 v[48:49], v[188:191], off offset:2040
	v_mov_b32_e32 v230, v46
	v_mov_b32_e32 v231, v47
	global_store_dwordx4 v[48:49], v[228:231], off offset:-8
	v_pk_mul_f32 v[46:47], v[34:35], v[58:59]
	v_ashrrev_i32_e32 v43, 31, v42
	v_lshlrev_b64 v[44:45], 11, v[42:43]
	v_lshl_add_u64 v[44:45], s[14:15], 0, v[44:45]
	v_lshl_add_u64 v[44:45], v[44:45], 0, v[146:147]
	s_nop 0
	v_add_f32_e32 v34, v46, v46
	v_add_f32_e32 v35, v47, v47
	v_mul_f32_e32 v34, 0x3fb8aa3b, v34
	v_mul_f32_e32 v35, 0x3fb8aa3b, v35
	v_exp_f32_e32 v34, v34
	v_exp_f32_e32 v35, v35
	v_sub_f32_e32 v34, 1.0, v34
	v_sub_f32_e32 v35, 1.0, v35
	v_max_f32_e32 v34, 0, v34
	v_max_f32_e32 v35, 0, v35
	v_sqrt_f32_e32 v34, v34
	v_sqrt_f32_e32 v35, v35
	s_nop 0
	v_mov_b32_e32 v44, v208
	v_mov_b32_e32 v45, v209
	v_lshlrev_b32_e32 v48, 16, v44
	v_and_b32_e32 v49, 0xffff0000, v44
	v_pk_mul_f32 v[34:35], v[38:39], v[34:35]
	v_lshlrev_b32_e32 v44, 16, v45
	v_pk_mul_f32 v[38:39], v[34:35], v[48:49]
	v_add_f32_e32 v35, v40, v68
	v_mul_f32_e32 v35, 0xbfb8aa3b, v35
	v_exp_f32_e32 v35, v35
	v_add_f32_e32 v34, v36, v72
	v_mul_f32_e32 v34, 0xbfb8aa3b, v34
	v_exp_f32_e32 v34, v34
	v_add_f32_e32 v35, 1.0, v35
	v_rcp_f32_e32 v36, v35
	v_add_f32_e32 v35, v37, v73
	v_mul_f32_e32 v35, 0xbfb8aa3b, v35
	v_exp_f32_e32 v35, v35
	v_add_f32_e32 v34, 1.0, v34
	v_rcp_f32_e32 v34, v34
	v_add_f32_e32 v37, v41, v69
	v_add_f32_e32 v35, 1.0, v35
	v_rcp_f32_e32 v35, v35
	v_mul_f32_e32 v37, 0xbfb8aa3b, v37
	v_exp_f32_e32 v37, v37
	v_and_b32_e32 v45, 0xffff0000, v45
	v_pk_mul_f32 v[40:41], v[34:35], v[60:61]
	v_cvt_pk_bf16_f32 v38, v38, v39
	v_add_f32_e32 v34, v40, v40
	v_add_f32_e32 v35, v41, v41
	v_mul_f32_e32 v34, 0x3fb8aa3b, v34
	v_mul_f32_e32 v35, 0x3fb8aa3b, v35
	v_exp_f32_e32 v34, v34
	v_exp_f32_e32 v35, v35
	v_add_f32_e32 v37, 1.0, v37
	v_rcp_f32_e32 v37, v37
	v_sub_f32_e32 v34, 1.0, v34
	v_sub_f32_e32 v35, 1.0, v35
	v_max_f32_e32 v34, 0, v34
	v_max_f32_e32 v35, 0, v35
	v_sqrt_f32_e32 v34, v34
	v_sqrt_f32_e32 v35, v35
	s_nop 0
	v_pk_mul_f32 v[34:35], v[36:37], v[34:35]
	s_nop 0
	v_pk_mul_f32 v[36:37], v[34:35], v[44:45]
	v_cvt_pk_bf16_f32 v45, v40, v41
	v_mad_i64_i32 v[40:41], s[6:7], v42, s84, v[130:131]
	v_lshl_add_u64 v[40:41], v[40:41], 0, v[62:63]
	v_add_co_u32_e32 v40, vcc, s69, v40
	v_add_u32_e32 v34, 0x50, v42
	v_cvt_pk_bf16_f32 v44, v46, v47
	v_addc_co_u32_e32 v41, vcc, 0, v41, vcc
	v_cvt_pk_bf16_f32 v39, v36, v37
	v_mov_b32_e32 v122, v44
	v_mov_b32_e32 v123, v45
	global_store_dwordx4 v[40:41], v[120:123], off offset:2040
	v_mov_b32_e32 v126, v38
	v_mov_b32_e32 v127, v39
	global_store_dwordx4 v[40:41], v[124:127], off offset:-8
	v_pk_mul_f32 v[38:39], v[26:27], v[58:59]
	v_ashrrev_i32_e32 v35, 31, v34
	v_lshlrev_b64 v[36:37], 11, v[34:35]
	v_lshl_add_u64 v[36:37], s[14:15], 0, v[36:37]
	v_lshl_add_u64 v[36:37], v[36:37], 0, v[146:147]
	s_nop 0
	v_add_f32_e32 v26, v38, v38
	v_add_f32_e32 v27, v39, v39
	v_mul_f32_e32 v26, 0x3fb8aa3b, v26
	v_mul_f32_e32 v27, 0x3fb8aa3b, v27
	v_exp_f32_e32 v26, v26
	v_exp_f32_e32 v27, v27
	v_sub_f32_e32 v26, 1.0, v26
	v_sub_f32_e32 v27, 1.0, v27
	v_max_f32_e32 v26, 0, v26
	v_max_f32_e32 v27, 0, v27
	v_sqrt_f32_e32 v26, v26
	v_sqrt_f32_e32 v27, v27
	s_nop 0
	v_mov_b32_e32 v36, v210
	v_mov_b32_e32 v37, v211
	v_lshlrev_b32_e32 v40, 16, v36
	v_and_b32_e32 v41, 0xffff0000, v36
	v_pk_mul_f32 v[26:27], v[30:31], v[26:27]
	v_lshlrev_b32_e32 v36, 16, v37
	v_pk_mul_f32 v[30:31], v[26:27], v[40:41]
	v_add_f32_e32 v27, v32, v68
	v_mul_f32_e32 v27, 0xbfb8aa3b, v27
	v_exp_f32_e32 v27, v27
	v_add_f32_e32 v26, v28, v72
	v_mul_f32_e32 v26, 0xbfb8aa3b, v26
	v_exp_f32_e32 v26, v26
	v_add_f32_e32 v27, 1.0, v27
	v_rcp_f32_e32 v28, v27
	v_add_f32_e32 v27, v29, v73
	v_mul_f32_e32 v27, 0xbfb8aa3b, v27
	v_exp_f32_e32 v27, v27
	v_add_f32_e32 v26, 1.0, v26
	v_rcp_f32_e32 v26, v26
	v_add_f32_e32 v29, v33, v69
	v_add_f32_e32 v27, 1.0, v27
	v_rcp_f32_e32 v27, v27
	v_mul_f32_e32 v29, 0xbfb8aa3b, v29
	v_exp_f32_e32 v29, v29
	v_and_b32_e32 v37, 0xffff0000, v37
	v_pk_mul_f32 v[32:33], v[26:27], v[60:61]
	v_cvt_pk_bf16_f32 v30, v30, v31
	v_add_f32_e32 v26, v32, v32
	v_add_f32_e32 v27, v33, v33
	v_mul_f32_e32 v26, 0x3fb8aa3b, v26
	v_mul_f32_e32 v27, 0x3fb8aa3b, v27
	v_exp_f32_e32 v26, v26
	v_exp_f32_e32 v27, v27
	v_add_f32_e32 v29, 1.0, v29
	v_rcp_f32_e32 v29, v29
	v_sub_f32_e32 v26, 1.0, v26
	v_sub_f32_e32 v27, 1.0, v27
	v_max_f32_e32 v26, 0, v26
	v_max_f32_e32 v27, 0, v27
	v_sqrt_f32_e32 v26, v26
	v_sqrt_f32_e32 v27, v27
	s_nop 0
	v_pk_mul_f32 v[26:27], v[28:29], v[26:27]
	s_nop 0
	v_pk_mul_f32 v[28:29], v[26:27], v[36:37]
	v_cvt_pk_bf16_f32 v37, v32, v33
	v_mad_i64_i32 v[32:33], s[6:7], v34, s84, v[130:131]
	v_lshl_add_u64 v[32:33], v[32:33], 0, v[62:63]
	v_add_co_u32_e32 v32, vcc, s69, v32
	v_add_u32_e32 v26, 16, v34
	v_cvt_pk_bf16_f32 v36, v38, v39
	v_addc_co_u32_e32 v33, vcc, 0, v33, vcc
	v_cvt_pk_bf16_f32 v31, v28, v29
	v_mov_b32_e32 v114, v36
	v_mov_b32_e32 v115, v37
	global_store_dwordx4 v[32:33], v[112:115], off offset:2040
	v_mov_b32_e32 v118, v30
	v_mov_b32_e32 v119, v31
	global_store_dwordx4 v[32:33], v[116:119], off offset:-8
	v_pk_mul_f32 v[30:31], v[18:19], v[58:59]
	v_ashrrev_i32_e32 v27, 31, v26
	v_lshlrev_b64 v[28:29], 11, v[26:27]
	v_lshl_add_u64 v[28:29], s[14:15], 0, v[28:29]
	v_lshl_add_u64 v[28:29], v[28:29], 0, v[146:147]
	s_nop 0
	v_add_f32_e32 v18, v30, v30
	v_add_f32_e32 v19, v31, v31
	v_mul_f32_e32 v18, 0x3fb8aa3b, v18
	v_mul_f32_e32 v19, 0x3fb8aa3b, v19
	v_exp_f32_e32 v18, v18
	v_exp_f32_e32 v19, v19
	v_sub_f32_e32 v18, 1.0, v18
	v_sub_f32_e32 v19, 1.0, v19
	v_max_f32_e32 v18, 0, v18
	v_max_f32_e32 v19, 0, v19
	v_sqrt_f32_e32 v18, v18
	v_sqrt_f32_e32 v19, v19
	s_nop 0
	v_mov_b32_e32 v28, v212
	v_mov_b32_e32 v29, v213
	v_lshlrev_b32_e32 v32, 16, v28
	v_and_b32_e32 v33, 0xffff0000, v28
	v_pk_mul_f32 v[18:19], v[22:23], v[18:19]
	v_lshlrev_b32_e32 v28, 16, v29
	v_pk_mul_f32 v[22:23], v[18:19], v[32:33]
	v_add_f32_e32 v19, v24, v68
	v_mul_f32_e32 v19, 0xbfb8aa3b, v19
	v_exp_f32_e32 v19, v19
	v_add_f32_e32 v18, v20, v72
	v_mul_f32_e32 v18, 0xbfb8aa3b, v18
	v_exp_f32_e32 v18, v18
	v_add_f32_e32 v19, 1.0, v19
	v_rcp_f32_e32 v20, v19
	v_add_f32_e32 v19, v21, v73
	v_mul_f32_e32 v19, 0xbfb8aa3b, v19
	v_exp_f32_e32 v19, v19
	v_add_f32_e32 v18, 1.0, v18
	v_rcp_f32_e32 v18, v18
	v_add_f32_e32 v21, v25, v69
	v_add_f32_e32 v19, 1.0, v19
	v_rcp_f32_e32 v19, v19
	v_mul_f32_e32 v21, 0xbfb8aa3b, v21
	v_exp_f32_e32 v21, v21
	v_and_b32_e32 v29, 0xffff0000, v29
	v_pk_mul_f32 v[24:25], v[18:19], v[60:61]
	v_cvt_pk_bf16_f32 v22, v22, v23
	v_add_f32_e32 v18, v24, v24
	v_add_f32_e32 v19, v25, v25
	v_mul_f32_e32 v18, 0x3fb8aa3b, v18
	v_mul_f32_e32 v19, 0x3fb8aa3b, v19
	v_exp_f32_e32 v18, v18
	v_exp_f32_e32 v19, v19
	v_add_f32_e32 v21, 1.0, v21
	v_rcp_f32_e32 v21, v21
	v_sub_f32_e32 v18, 1.0, v18
	v_sub_f32_e32 v19, 1.0, v19
	v_max_f32_e32 v18, 0, v18
	v_max_f32_e32 v19, 0, v19
	v_sqrt_f32_e32 v18, v18
	v_sqrt_f32_e32 v19, v19
	s_nop 0
	v_pk_mul_f32 v[18:19], v[20:21], v[18:19]
	s_nop 0
	v_pk_mul_f32 v[20:21], v[18:19], v[28:29]
	v_cvt_pk_bf16_f32 v29, v24, v25
	v_mad_i64_i32 v[24:25], s[6:7], v26, s84, v[130:131]
	v_lshl_add_u64 v[24:25], v[24:25], 0, v[62:63]
	v_add_co_u32_e32 v24, vcc, s69, v24
	v_add_u32_e32 v18, 16, v26
	v_cvt_pk_bf16_f32 v28, v30, v31
	v_addc_co_u32_e32 v25, vcc, 0, v25, vcc
	v_cvt_pk_bf16_f32 v23, v20, v21
	v_mov_b32_e32 v106, v28
	v_mov_b32_e32 v107, v29
	global_store_dwordx4 v[24:25], v[104:107], off offset:2040
	v_mov_b32_e32 v110, v22
	v_mov_b32_e32 v111, v23
	global_store_dwordx4 v[24:25], v[108:111], off offset:-8
	v_pk_mul_f32 v[22:23], v[10:11], v[58:59]
	v_ashrrev_i32_e32 v19, 31, v18
	v_lshlrev_b64 v[20:21], 11, v[18:19]
	v_lshl_add_u64 v[20:21], s[14:15], 0, v[20:21]
	v_lshl_add_u64 v[20:21], v[20:21], 0, v[146:147]
	s_nop 0
	v_add_f32_e32 v10, v22, v22
	v_add_f32_e32 v11, v23, v23
	v_mul_f32_e32 v10, 0x3fb8aa3b, v10
	v_mul_f32_e32 v11, 0x3fb8aa3b, v11
	v_exp_f32_e32 v10, v10
	v_exp_f32_e32 v11, v11
	v_sub_f32_e32 v10, 1.0, v10
	v_sub_f32_e32 v11, 1.0, v11
	v_max_f32_e32 v10, 0, v10
	v_max_f32_e32 v11, 0, v11
	v_sqrt_f32_e32 v10, v10
	v_sqrt_f32_e32 v11, v11
	s_nop 0
	v_mov_b32_e32 v20, v214
	v_mov_b32_e32 v21, v215
	v_lshlrev_b32_e32 v24, 16, v20
	v_and_b32_e32 v25, 0xffff0000, v20
	v_pk_mul_f32 v[10:11], v[14:15], v[10:11]
	v_lshlrev_b32_e32 v20, 16, v21
	v_pk_mul_f32 v[14:15], v[10:11], v[24:25]
	v_add_f32_e32 v11, v16, v68
	v_mul_f32_e32 v11, 0xbfb8aa3b, v11
	v_exp_f32_e32 v11, v11
	v_add_f32_e32 v10, v12, v72
	v_mul_f32_e32 v10, 0xbfb8aa3b, v10
	v_exp_f32_e32 v10, v10
	v_add_f32_e32 v11, 1.0, v11
	v_rcp_f32_e32 v12, v11
	v_add_f32_e32 v11, v13, v73
	v_mul_f32_e32 v11, 0xbfb8aa3b, v11
	v_exp_f32_e32 v11, v11
	v_add_f32_e32 v10, 1.0, v10
	v_rcp_f32_e32 v10, v10
	v_add_f32_e32 v13, v17, v69
	v_add_f32_e32 v11, 1.0, v11
	v_rcp_f32_e32 v11, v11
	v_mul_f32_e32 v13, 0xbfb8aa3b, v13
	v_exp_f32_e32 v13, v13
	v_and_b32_e32 v21, 0xffff0000, v21
	v_pk_mul_f32 v[16:17], v[10:11], v[60:61]
	v_cvt_pk_bf16_f32 v14, v14, v15
	v_add_f32_e32 v10, v16, v16
	v_add_f32_e32 v11, v17, v17
	v_mul_f32_e32 v10, 0x3fb8aa3b, v10
	v_mul_f32_e32 v11, 0x3fb8aa3b, v11
	v_exp_f32_e32 v10, v10
	v_exp_f32_e32 v11, v11
	v_add_f32_e32 v13, 1.0, v13
	v_rcp_f32_e32 v13, v13
	v_sub_f32_e32 v10, 1.0, v10
	v_sub_f32_e32 v11, 1.0, v11
	v_max_f32_e32 v10, 0, v10
	v_max_f32_e32 v11, 0, v11
	v_sqrt_f32_e32 v10, v10
	v_sqrt_f32_e32 v11, v11
	s_nop 0
	v_pk_mul_f32 v[10:11], v[12:13], v[10:11]
	s_nop 0
	v_pk_mul_f32 v[12:13], v[10:11], v[20:21]
	v_cvt_pk_bf16_f32 v21, v16, v17
	v_mad_i64_i32 v[16:17], s[6:7], v18, s84, v[130:131]
	v_lshl_add_u64 v[16:17], v[16:17], 0, v[62:63]
	v_add_co_u32_e32 v16, vcc, s69, v16
	v_add_u32_e32 v10, 16, v18
	v_cvt_pk_bf16_f32 v20, v22, v23
	v_addc_co_u32_e32 v17, vcc, 0, v17, vcc
	v_cvt_pk_bf16_f32 v15, v12, v13
	v_mov_b32_e32 v98, v20
	v_mov_b32_e32 v99, v21
	global_store_dwordx4 v[16:17], v[96:99], off offset:2040
	v_mov_b32_e32 v102, v14
	v_mov_b32_e32 v103, v15
	global_store_dwordx4 v[16:17], v[100:103], off offset:-8
	s_nop 0
	v_ashrrev_i32_e32 v11, 31, v10
	v_lshlrev_b64 v[12:13], 11, v[10:11]
	v_lshl_add_u64 v[12:13], s[14:15], 0, v[12:13]
	v_lshl_add_u64 v[12:13], v[12:13], 0, v[146:147]
	s_nop 0
	v_add_f32_e32 v11, v2, v2
	v_mul_f32_e32 v11, 0x3fb8aa3b, v11
	v_exp_f32_e32 v11, v11
	v_cvt_pk_bf16_f32 v2, v2, v3
	v_sub_f32_e32 v11, 1.0, v11
	v_max_f32_e32 v11, 0, v11
	v_sqrt_f32_e32 v14, v11
	v_add_f32_e32 v11, v3, v3
	v_mul_f32_e32 v11, 0x3fb8aa3b, v11
	v_exp_f32_e32 v11, v11
	v_cvt_pk_bf16_f32 v3, v4, v5
	v_sub_f32_e32 v11, 1.0, v11
	v_max_f32_e32 v11, 0, v11
	v_sqrt_f32_e32 v15, v11
	v_add_f32_e32 v11, v4, v4
	v_mul_f32_e32 v11, 0x3fb8aa3b, v11
	v_exp_f32_e32 v11, v11
	v_pk_mul_f32 v[6:7], v[6:7], v[14:15]
	v_sub_f32_e32 v11, 1.0, v11
	v_max_f32_e32 v11, 0, v11
	v_sqrt_f32_e32 v14, v11
	v_add_f32_e32 v11, v5, v5
	v_mul_f32_e32 v11, 0x3fb8aa3b, v11
	v_exp_f32_e32 v11, v11
	v_mad_i64_i32 v[4:5], s[6:7], v10, s84, v[130:131]
	v_lshl_add_u64 v[4:5], v[4:5], 0, v[62:63]
	v_sub_f32_e32 v11, 1.0, v11
	v_max_f32_e32 v11, 0, v11
	v_sqrt_f32_e32 v15, v11
	v_add_co_u32_e32 v4, vcc, s69, v4
	v_pk_mul_f32 v[8:9], v[8:9], v[14:15]
	s_nop 0
	v_addc_co_u32_e32 v5, vcc, 0, v5, vcc
	v_mov_b32_e32 v90, v2
	v_mov_b32_e32 v91, v3
	global_store_dwordx4 v[4:5], v[88:91], off offset:2040
	s_andn2_b64 vcc, exec, s[4:5]
	s_nop 0
	v_mov_b32_e32 v12, v216
	v_mov_b32_e32 v13, v217
	v_lshlrev_b32_e32 v16, 16, v12
	v_and_b32_e32 v17, 0xffff0000, v12
	v_lshlrev_b32_e32 v12, 16, v13
	v_and_b32_e32 v13, 0xffff0000, v13
	v_pk_mul_f32 v[6:7], v[6:7], v[16:17]
	v_pk_mul_f32 v[8:9], v[8:9], v[12:13]
	v_cvt_pk_bf16_f32 v2, v6, v7
	v_cvt_pk_bf16_f32 v3, v8, v9
	v_mov_b32_e32 v94, v2
	v_mov_b32_e32 v95, v3
	global_store_dwordx4 v[4:5], v[92:95], off offset:-8
	s_cbranch_vccz .LBB0_1214
